# v58 plus dead -1e30 defaults removed and NA steady score tiles issue the 4 K-fragment and 4 bias LDS reads together with counted lgkmcnt waits
# baseline (speedup 1.0000x reference)
; template <int L>
; __device__ __forceinline__ void layer_body(const Args& args, LAS unsigned char* lds, const int wave, const int G, const int gw, const int NGW, const int lo, const int hi,
;                                            unsigned char* const ws_kernel, const XcdBarrier& bar, int& pid) {
;     ...
;                     if (tl_ < 15 * 31) rl[tl_] = rpb[h * 15 * 31 + tl_];
;                     __syncthreads();
.LBB0_846:
	s_or_b64 exec, exec, s[0:1]
	s_add_i32 s0, s81, s84
	s_and_b32 s14, s0, 28
	s_max_u32 s0, s14, 4
	v_med3_u32 v0, s14, 1, 25
	v_add_u32_e32 v4, 32, v77
	v_add_u32_e32 v8, 64, v77
	v_add_u32_e32 v12, 0x60, v77
	v_add_u32_e32 v16, 0x80, v77
	v_add_u32_e32 v20, 0xa0, v77
	v_add_u32_e32 v40, 0xc0, v77
	v_add_u32_e32 v44, 0xe0, v77
	v_add_u32_e32 v48, 0x100, v77
	v_add_u32_e32 v52, 0x120, v77
	v_add_u32_e32 v56, 0x140, v77
	v_add_u32_e32 v60, 0x160, v77
	v_add_u32_e32 v64, 0x180, v77
	v_add_u32_e32 v70, 0x1a0, v77
	s_and_b32 s1, s21, 1
	s_lshl_b32 s6, s36, 8
	v_subrev_u32_e32 v0, s0, v0
	s_add_u32 s6, s57, s6
	v_add_u32_e32 v72, 10, v0
	v_mul_hi_i32 v0, v77, s9
	v_mul_hi_i32 v5, v4, s9
	v_mul_hi_i32 v9, v8, s9
	v_mul_hi_i32 v13, v12, s9
	v_mul_hi_i32 v17, v16, s9
	v_mul_hi_i32 v21, v20, s9
	v_mul_hi_i32 v41, v40, s9
	v_mul_hi_i32 v45, v44, s9
	v_mul_hi_i32 v49, v48, s9
	v_mul_hi_i32 v53, v52, s9
	v_mul_hi_i32 v57, v56, s9
	v_mul_hi_i32 v61, v60, s9
	v_mul_hi_i32 v65, v64, s9
	v_mul_hi_i32 v73, v70, s9
	s_addc_u32 s7, s58, 0
	v_lshrrev_b32_e32 v1, 31, v0
	v_ashrrev_i32_e32 v0, 4, v0
	v_lshrrev_b32_e32 v6, 31, v5
	v_ashrrev_i32_e32 v5, 4, v5
	v_lshrrev_b32_e32 v10, 31, v9
	v_ashrrev_i32_e32 v9, 4, v9
	v_lshrrev_b32_e32 v14, 31, v13
	v_ashrrev_i32_e32 v13, 4, v13
	v_lshrrev_b32_e32 v18, 31, v17
	v_ashrrev_i32_e32 v17, 4, v17
	v_lshrrev_b32_e32 v22, 31, v21
	v_ashrrev_i32_e32 v21, 4, v21
	v_lshrrev_b32_e32 v42, 31, v41
	v_ashrrev_i32_e32 v41, 4, v41
	v_lshrrev_b32_e32 v46, 31, v45
	v_ashrrev_i32_e32 v45, 4, v45
	v_lshrrev_b32_e32 v50, 31, v49
	v_ashrrev_i32_e32 v49, 4, v49
	v_lshrrev_b32_e32 v54, 31, v53
	v_ashrrev_i32_e32 v53, 4, v53
	v_lshrrev_b32_e32 v58, 31, v57
	v_ashrrev_i32_e32 v57, 4, v57
	v_lshrrev_b32_e32 v62, 31, v61
	v_ashrrev_i32_e32 v61, 4, v61
	v_lshrrev_b32_e32 v66, 31, v65
	v_ashrrev_i32_e32 v65, 4, v65
	v_lshrrev_b32_e32 v74, 31, v73
	v_ashrrev_i32_e32 v73, 4, v73
	v_lshl_add_u64 v[68:69], s[6:7], 0, v[104:105]
	s_add_i32 s6, s85, s96
	v_add_u32_e32 v78, v0, v1
	v_add_u32_e32 v80, v5, v6
	v_add_u32_e32 v82, v9, v10
	v_add_u32_e32 v84, v13, v14
	v_add_u32_e32 v86, v17, v18
	v_add_u32_e32 v88, v21, v22
	v_add_u32_e32 v90, v41, v42
	v_add_u32_e32 v92, v45, v46
	v_add_u32_e32 v94, v49, v50
	v_add_u32_e32 v96, v53, v54
	v_add_u32_e32 v98, v57, v58
	v_add_u32_e32 v100, v61, v62
	v_add_u32_e32 v102, v65, v66
	v_add_u32_e32 v113, v73, v74
	v_sub_u32_e64 v71, s14, 4 clamp
	s_and_b32 s60, s6, 0xfffff800
	s_mul_i32 s6, s1, 24
	v_min_i32_e32 v0, v78, v72
	v_min_i32_e32 v5, v80, v72
	v_min_i32_e32 v9, v82, v72
	v_min_i32_e32 v13, v84, v72
	v_min_i32_e32 v17, v86, v72
	v_min_i32_e32 v21, v88, v72
	v_min_i32_e32 v41, v90, v72
	v_min_i32_e32 v45, v92, v72
	v_min_i32_e32 v49, v94, v72
	v_min_i32_e32 v53, v96, v72
	v_min_i32_e32 v57, v98, v72
	v_min_i32_e32 v61, v100, v72
	v_min_i32_e32 v65, v102, v72
	v_min_i32_e32 v72, v113, v72
	s_or_b32 s8, s60, s6
	v_add_lshl_u32 v0, v0, v71, 6
	v_mad_i32_i24 v79, v78, s88, v77
	v_add_lshl_u32 v5, v5, v71, 6
	v_mad_i32_i24 v81, v80, s88, v4
	v_add_lshl_u32 v9, v9, v71, 6
	v_mad_i32_i24 v83, v82, s88, v8
	v_add_lshl_u32 v13, v13, v71, 6
	v_mad_i32_i24 v85, v84, s88, v12
	v_add_lshl_u32 v17, v17, v71, 6
	v_mad_i32_i24 v87, v86, s88, v16
	v_add_lshl_u32 v21, v21, v71, 6
	v_mad_i32_i24 v89, v88, s88, v20
	v_add_lshl_u32 v41, v41, v71, 6
	v_mad_i32_i24 v91, v90, s88, v40
	v_add_lshl_u32 v45, v45, v71, 6
	v_mad_i32_i24 v93, v92, s88, v44
	v_add_lshl_u32 v49, v49, v71, 6
	v_mad_i32_i24 v95, v94, s88, v48
	v_add_lshl_u32 v53, v53, v71, 6
	v_mad_i32_i24 v97, v96, s88, v52
	v_add_lshl_u32 v57, v57, v71, 6
	v_mad_i32_i24 v99, v98, s88, v56
	v_add_lshl_u32 v61, v61, v71, 6
	v_mad_i32_i24 v101, v100, s88, v60
	v_add_lshl_u32 v65, v65, v71, 6
	v_mad_i32_i24 v103, v102, s88, v64
	v_add_lshl_u32 v71, v72, v71, 6
	v_mad_i32_i24 v114, v113, s88, v70
	v_add3_u32 v0, v79, s8, v0
	v_add3_u32 v4, v81, s8, v5
	v_add3_u32 v8, v83, s8, v9
	v_add3_u32 v12, v85, s8, v13
	v_add3_u32 v16, v87, s8, v17
	v_add3_u32 v20, v89, s8, v21
	v_add3_u32 v40, v91, s8, v41
	v_add3_u32 v44, v93, s8, v45
	v_add3_u32 v48, v95, s8, v49
	v_add3_u32 v52, v97, s8, v53
	v_add3_u32 v56, v99, s8, v57
	v_add3_u32 v60, v101, s8, v61
	v_add3_u32 v64, v103, s8, v65
	v_add3_u32 v70, v114, s8, v71
	v_mad_i64_i32 v[0:1], s[6:7], v0, s22, v[68:69]
	v_mad_i64_i32 v[4:5], s[6:7], v4, s22, v[68:69]
	v_mad_i64_i32 v[8:9], s[6:7], v8, s22, v[68:69]
	v_mad_i64_i32 v[12:13], s[6:7], v12, s22, v[68:69]
	v_mad_i64_i32 v[16:17], s[6:7], v16, s22, v[68:69]
	v_mad_i64_i32 v[20:21], s[6:7], v20, s22, v[68:69]
	v_mad_i64_i32 v[40:41], s[6:7], v40, s22, v[68:69]
	v_mad_i64_i32 v[44:45], s[6:7], v44, s22, v[68:69]
	v_mad_i64_i32 v[48:49], s[6:7], v48, s22, v[68:69]
	v_mad_i64_i32 v[52:53], s[6:7], v52, s22, v[68:69]
	v_mad_i64_i32 v[56:57], s[6:7], v56, s22, v[68:69]
	v_mad_i64_i32 v[60:61], s[6:7], v60, s22, v[68:69]
	v_mad_i64_i32 v[64:65], s[6:7], v64, s22, v[68:69]
	v_mad_i64_i32 v[68:69], s[6:7], v70, s22, v[68:69]
	s_waitcnt lgkmcnt(0)
	s_barrier
; #define LAS __attribute__((address_space(3)))
; template <int L>
; __device__ __forceinline__ void layer_body(const Args& args, LAS unsigned char* lds, const int wave, const int G, const int gw, const int NGW, const int lo, const int hi,
;                                            unsigned char* const ws_kernel, const XcdBarrier& bar, int& pid) {
;     ...
;                     NA_LOADROWS(unit, rst, 2 * D);
;                     const int rr = wave >> 1, cb = 2 * hc + (wave & 1), r = rbase + rr, r0w = min(max(r - 4, 0), 24), cs = min(max(16 * cb - 8, 0), 32), coloff = cs - 24 * hc;
;                     const int c = 16 * cb + qi, wsq = min(max(c - 8, 0), 48);
;                     f32x4 sc[16];
; #pragma unroll
;                     for (int t = 0; t < 16; ++t) {
;                         const int irow = (r0w - krlo + (t >> 1)) * 40 + coloff + 16 * (t & 1);
;                         const unsigned ka = IMG + (unsigned)((irow + qi) * KPITCH + 16 * kg);
;                         f32x4 a = (f32x4){0.f, 0.f, 0.f, 0.f};
; #pragma unroll
;                         for (int ks = 0; ks < 4; ++ks) a = __builtin_amdgcn_mfma_f32_16x16x32_bf16(*(const LAS bf16x8*)(size_t)(ka + 64 * ks), qfn[ks], a, 0, 0, 0);
;                         const int dr = r0w + (t >> 1) - r + 7;
; #pragma unroll
;                         for (int j = 0; j < 4; ++j) { const int kc = cs + 16 * (t & 1) + 4 * kg + j; const bool valid = (kc >= wsq) && (kc < wsq + 16); const int dc = min(max(kc - c + 15, 0), 30);
;                             sc[t][j] = valid ? a[j] * scale_log2 + rl[dr * 31 + dc] * LOG2E : -1e30f; }
	global_load_dwordx4 v[0:3], v[0:1], off
	s_add_i32 s14, s14, s53
	global_load_dwordx4 v[4:7], v[4:5], off
	s_lshl_b32 s7, s1, 5
	global_load_dwordx4 v[8:11], v[8:9], off
	s_max_i32 s6, s14, 4
	global_load_dwordx4 v[12:15], v[12:13], off
	s_or_b32 s7, s7, s54
	global_load_dwordx4 v[16:19], v[16:17], off
	s_add_i32 s6, s6, -4
	global_load_dwordx4 v[20:23], v[20:21], off
	s_max_i32 s8, s7, 8
	global_load_dwordx4 v[40:43], v[40:41], off
	s_min_u32 s6, s6, 24
	global_load_dwordx4 v[44:47], v[44:45], off
	s_add_i32 s8, s8, -8
	global_load_dwordx4 v[48:51], v[48:49], off
	s_min_u32 s8, s8, 32
	global_load_dwordx4 v[52:55], v[52:53], off
	s_mulk_i32 s1, 0xffe8
	global_load_dwordx4 v[56:59], v[56:57], off
	v_or_b32_e32 v109, s7, v112
	global_load_dwordx4 v[60:63], v[60:61], off
	s_sub_i32 s41, s6, s0
	global_load_dwordx4 v[64:67], v[64:65], off
	s_add_i32 s15, s8, s1
	global_load_dwordx4 v[68:71], v[68:69], off
	v_max_i32_e32 v72, 8, v109
	s_mul_i32 s41, s41, 40
	v_bfe_u32 v76, v111, 4, 2
	v_add_u32_e32 v72, -8, v72
	v_add_u32_e32 v121, s15, v112
	s_sub_i32 s0, s6, s14
	s_add_i32 s6, s41, 0xa0
	v_min_u32_e32 v129, 48, v72
	v_lshl_add_u32 v118, v76, 4, 0
	v_add_u32_e32 v72, s6, v121
	v_mad_i32_i24 v104, v72, s90, v118
	ds_read_b128 v[72:75], v104
	ds_read_b128 v[122:125], v104 offset:64
	s_waitcnt lgkmcnt(1)
	v_mfma_f32_16x16x32_bf16 v[72:75], v[72:75], v[24:27], 0
	v_lshlrev_b32_e32 v110, 2, v76
	v_add_u32_e32 v134, s8, v110
	v_add_u32_e32 v131, 16, v129
	s_waitcnt lgkmcnt(0)
	v_mfma_f32_16x16x32_bf16 v[72:75], v[122:125], v[28:31], v[72:75]
	ds_read_b128 v[122:125], v104 offset:128
	s_mulk_i32 s0, 0x7c
	s_add_i32 s42, s0, 0
	s_waitcnt lgkmcnt(0)
	v_mfma_f32_16x16x32_bf16 v[72:75], v[122:125], v[32:35], v[72:75]
	ds_read_b128 v[122:125], v104 offset:192
	v_cmp_ge_u32_e32 vcc, v134, v129
	v_cmp_lt_u32_e64 s[0:1], v134, v131
	s_waitcnt lgkmcnt(0)
	v_mfma_f32_16x16x32_bf16 v[72:75], v[122:125], v[36:39], v[72:75]
	v_sub_u32_e32 v115, v134, v109
	s_add_i32 s42, s42, 0x1dc00
	s_and_b64 s[64:65], vcc, s[0:1]
	v_max_i32_e32 v124, -15, v115
	v_mov_b32_e32 v204, 0xf149f2ca
	s_nop 1
	v_add_u32_e32 v201, 15, v124
	v_min_u32_e32 v201, 30, v201
	v_lshl_add_u32 v216, v201, 2, s42
	ds_read_b32 v201, v216 offset:868
	s_nop 0
	s_waitcnt lgkmcnt(0)
	v_fma_f32 v200, v72, s62, v201
	v_cndmask_b32_e64 v115, v204, v200, s[64:65]
	v_or_b32_e32 v72, 1, v134
	v_cmp_ge_u32_e32 vcc, v72, v129
	v_cmp_lt_u32_e64 s[0:1], v72, v131
	v_sub_u32_e32 v72, v72, v109
	s_and_b64 s[66:67], vcc, s[0:1]
	v_max_i32_e32 v125, -15, v72
	s_nop 1
	v_add_u32_e32 v203, 15, v125
	v_min_u32_e32 v203, 30, v203
	v_lshl_add_u32 v217, v203, 2, s42
	ds_read_b32 v203, v217 offset:868
	s_nop 0
	s_waitcnt lgkmcnt(0)
	v_fma_f32 v202, v73, s62, v203
	v_cndmask_b32_e64 v104, v204, v202, s[66:67]
	v_or_b32_e32 v72, 2, v134
	v_cmp_ge_u32_e32 vcc, v72, v129
	v_cmp_lt_u32_e64 s[0:1], v72, v131
	v_sub_u32_e32 v72, v72, v109
	s_and_b64 s[68:69], vcc, s[0:1]
	v_max_i32_e32 v126, -15, v72
	s_nop 1
	v_add_u32_e32 v213, 15, v126
	v_min_u32_e32 v213, 30, v213
	v_lshl_add_u32 v218, v213, 2, s42
	ds_read_b32 v213, v218 offset:868
	s_nop 0
	s_waitcnt lgkmcnt(0)
	v_fma_f32 v212, v74, s62, v213
	v_cndmask_b32_e64 v117, v204, v212, s[68:69]
	v_or_b32_e32 v72, 3, v134
	v_cmp_ge_u32_e32 vcc, v72, v129
	v_cmp_lt_u32_e64 s[0:1], v72, v131
	v_sub_u32_e32 v72, v72, v109
	s_and_b64 s[70:71], vcc, s[0:1]
	v_max_i32_e32 v127, -15, v72
	s_nop 1
	v_add_u32_e32 v215, 15, v127
	v_min_u32_e32 v215, 30, v215
	v_lshl_add_u32 v219, v215, 2, s42
	ds_read_b32 v215, v219 offset:868
	s_nop 0
	s_waitcnt lgkmcnt(0)
	v_fma_f32 v214, v75, s62, v215
	v_cndmask_b32_e64 v116, v204, v214, s[70:71]
	v_add_u32_e32 v128, 16, v121
	v_add_u32_e32 v72, s6, v128
	v_mad_i32_i24 v119, v72, s90, v118
	ds_read_b128 v[72:75], v119
	ds_read_b128 v[136:139], v119 offset:64
	v_add_u32_e32 v120, 16, v134
	v_cmp_ge_u32_e32 vcc, v120, v129
	v_cmp_lt_u32_e64 s[0:1], v134, v129
	v_sub_u32_e32 v120, v120, v109
	s_and_b64 s[72:73], vcc, s[0:1]
	v_max_i32_e32 v130, -15, v120
	s_waitcnt lgkmcnt(1)
	v_mfma_f32_16x16x32_bf16 v[72:75], v[72:75], v[24:27], 0
	s_waitcnt lgkmcnt(0)
	v_mfma_f32_16x16x32_bf16 v[72:75], v[136:139], v[28:31], v[72:75]
	ds_read_b128 v[136:139], v119 offset:128
	s_waitcnt lgkmcnt(0)
	v_mfma_f32_16x16x32_bf16 v[72:75], v[136:139], v[32:35], v[72:75]
	ds_read_b128 v[136:139], v119 offset:192
	s_waitcnt lgkmcnt(0)
	v_mfma_f32_16x16x32_bf16 v[72:75], v[136:139], v[36:39], v[72:75]
	s_nop 1
	v_add_u32_e32 v201, 15, v130
	v_min_u32_e32 v201, 30, v201
	v_lshl_add_u32 v220, v201, 2, s42
	ds_read_b32 v201, v220 offset:868
	s_nop 1
	s_nop 0
	s_waitcnt lgkmcnt(0)
	v_fma_f32 v200, v72, s62, v201
	v_cndmask_b32_e64 v120, v204, v200, s[72:73]
	s_nop 4
	v_add_u32_e32 v72, 17, v134
	v_cmp_ge_u32_e32 vcc, v72, v129
	v_cmp_lt_u32_e64 s[0:1], v72, v131
	v_sub_u32_e32 v72, v72, v109
	s_and_b64 s[74:75], vcc, s[0:1]
	v_max_i32_e32 v132, -15, v72
	s_nop 1
	v_add_u32_e32 v203, 15, v132
	v_min_u32_e32 v203, 30, v203
	v_lshl_add_u32 v221, v203, 2, s42
	ds_read_b32 v203, v221 offset:868
	s_nop 0
	s_waitcnt lgkmcnt(0)
	v_fma_f32 v202, v73, s62, v203
	v_cndmask_b32_e64 v119, v204, v202, s[74:75]
	v_add_u32_e32 v72, 18, v134
	v_cmp_ge_u32_e32 vcc, v72, v129
	v_cmp_lt_u32_e64 s[0:1], v72, v131
	v_sub_u32_e32 v72, v72, v109
	s_and_b64 s[76:77], vcc, s[0:1]
	v_max_i32_e32 v133, -15, v72
	s_nop 1
	v_add_u32_e32 v213, 15, v133
	v_min_u32_e32 v213, 30, v213
	v_lshl_add_u32 v222, v213, 2, s42
	ds_read_b32 v213, v222 offset:868
	s_nop 0
	s_waitcnt lgkmcnt(0)
; #define LAS __attribute__((address_space(3)))
; template <int L>
; __device__ __forceinline__ void layer_body(const Args& args, LAS unsigned char* lds, const int wave, const int G, const int gw, const int NGW, const int lo, const int hi,
;                                            unsigned char* const ws_kernel, const XcdBarrier& bar, int& pid) {
;     ...
; #pragma unroll
;                     for (int t = 0; t < 16; ++t) {
;                         const int irow = (r0w - krlo + (t >> 1)) * 40 + coloff + 16 * (t & 1);
;                         const unsigned ka = IMG + (unsigned)((irow + qi) * KPITCH + 16 * kg);
;                         f32x4 a = (f32x4){0.f, 0.f, 0.f, 0.f};
; #pragma unroll
;                         for (int ks = 0; ks < 4; ++ks) a = __builtin_amdgcn_mfma_f32_16x16x32_bf16(*(const LAS bf16x8*)(size_t)(ka + 64 * ks), qfn[ks], a, 0, 0, 0);
;                         const int dr = r0w + (t >> 1) - r + 7;
; #pragma unroll
;                         for (int j = 0; j < 4; ++j) { const int kc = cs + 16 * (t & 1) + 4 * kg + j; const bool valid = (kc >= wsq) && (kc < wsq + 16); const int dc = min(max(kc - c + 15, 0), 30);
;                             sc[t][j] = valid ? a[j] * scale_log2 + rl[dr * 31 + dc] * LOG2E : -1e30f; }
;                         __builtin_amdgcn_sched_barrier(0);
;                     }
	v_fma_f32 v212, v74, s62, v213
	v_cndmask_b32_e64 v123, v204, v212, s[76:77]
	v_add_u32_e32 v72, 19, v134
	v_cmp_ge_u32_e32 vcc, v72, v129
	v_cmp_lt_u32_e64 s[0:1], v72, v131
	v_sub_u32_e32 v72, v72, v109
	s_and_b64 s[0:1], vcc, s[0:1]
	v_max_i32_e32 v134, -15, v72
	s_nop 1
	v_add_u32_e32 v215, 15, v134
	v_min_u32_e32 v215, 30, v215
	v_lshl_add_u32 v223, v215, 2, s42
	ds_read_b32 v215, v223 offset:868
	s_nop 0
	s_waitcnt lgkmcnt(0)
	v_fma_f32 v214, v75, s62, v215
	v_cndmask_b32_e64 v122, v204, v214, s[0:1]
	s_add_i32 s7, s41, 0xc8
	v_add_u32_e32 v72, s7, v121
	v_mad_i32_i24 v129, v72, s90, v118
	ds_read_b128 v[72:75], v129
	ds_read_b128 v[136:139], v129 offset:64
	ds_read_b128 v[224:227], v129 offset:128
	ds_read_b128 v[228:231], v129 offset:192
	ds_read_b32 v201, v216 offset:992
	ds_read_b32 v203, v217 offset:992
	ds_read_b32 v213, v218 offset:992
	ds_read_b32 v215, v219 offset:992
	s_waitcnt lgkmcnt(7)
	v_mfma_f32_16x16x32_bf16 v[72:75], v[72:75], v[24:27], 0
	s_waitcnt lgkmcnt(6)
	v_mfma_f32_16x16x32_bf16 v[72:75], v[136:139], v[28:31], v[72:75]
	s_waitcnt lgkmcnt(5)
	v_mfma_f32_16x16x32_bf16 v[72:75], v[224:227], v[32:35], v[72:75]
	s_waitcnt lgkmcnt(4)
	v_mfma_f32_16x16x32_bf16 v[72:75], v[228:231], v[36:39], v[72:75]
	s_nop 7
	s_waitcnt lgkmcnt(0)
	v_fma_f32 v200, v72, s62, v201
	v_fma_f32 v202, v73, s62, v203
	v_fma_f32 v212, v74, s62, v213
	v_fma_f32 v214, v75, s62, v215
	v_cndmask_b32_e64 v131, v204, v200, s[64:65]
	v_cndmask_b32_e64 v129, v204, v202, s[66:67]
	v_cndmask_b32_e64 v136, v204, v212, s[68:69]
	v_cndmask_b32_e64 v135, v204, v214, s[70:71]
	v_add_u32_e32 v72, s7, v128
	v_mad_i32_i24 v137, v72, s90, v118
	ds_read_b128 v[72:75], v137
	ds_read_b128 v[138:141], v137 offset:64
	ds_read_b128 v[224:227], v137 offset:128
	ds_read_b128 v[228:231], v137 offset:192
	ds_read_b32 v201, v220 offset:992
	ds_read_b32 v203, v221 offset:992
	ds_read_b32 v213, v222 offset:992
	ds_read_b32 v215, v223 offset:992
	s_waitcnt lgkmcnt(7)
	v_mfma_f32_16x16x32_bf16 v[72:75], v[72:75], v[24:27], 0
	s_waitcnt lgkmcnt(6)
	v_mfma_f32_16x16x32_bf16 v[72:75], v[138:141], v[28:31], v[72:75]
	s_waitcnt lgkmcnt(5)
	v_mfma_f32_16x16x32_bf16 v[72:75], v[224:227], v[32:35], v[72:75]
	s_waitcnt lgkmcnt(4)
	v_mfma_f32_16x16x32_bf16 v[72:75], v[228:231], v[36:39], v[72:75]
	s_nop 7
	s_waitcnt lgkmcnt(0)
	v_fma_f32 v200, v72, s62, v201
	v_fma_f32 v202, v73, s62, v203
	v_fma_f32 v212, v74, s62, v213
	v_fma_f32 v214, v75, s62, v215
	v_cndmask_b32_e64 v138, v204, v200, s[72:73]
	v_cndmask_b32_e64 v137, v204, v202, s[74:75]
	v_cndmask_b32_e64 v140, v204, v212, s[76:77]
	v_cndmask_b32_e64 v139, v204, v214, s[0:1]
	s_add_i32 s8, s41, 0xf0
	v_add_u32_e32 v72, s8, v121
	v_mad_i32_i24 v141, v72, s90, v118
	ds_read_b128 v[72:75], v141
	ds_read_b128 v[142:145], v141 offset:64
	ds_read_b128 v[224:227], v141 offset:128
	ds_read_b128 v[228:231], v141 offset:192
	ds_read_b32 v201, v216 offset:1116
	ds_read_b32 v203, v217 offset:1116
	ds_read_b32 v213, v218 offset:1116
	ds_read_b32 v215, v219 offset:1116
	s_waitcnt lgkmcnt(7)
	v_mfma_f32_16x16x32_bf16 v[72:75], v[72:75], v[24:27], 0
	s_waitcnt lgkmcnt(6)
	v_mfma_f32_16x16x32_bf16 v[72:75], v[142:145], v[28:31], v[72:75]
	s_waitcnt lgkmcnt(5)
	v_mfma_f32_16x16x32_bf16 v[72:75], v[224:227], v[32:35], v[72:75]
	s_waitcnt lgkmcnt(4)
	v_mfma_f32_16x16x32_bf16 v[72:75], v[228:231], v[36:39], v[72:75]
	s_nop 7
	s_waitcnt lgkmcnt(0)
	v_fma_f32 v200, v72, s62, v201
	v_fma_f32 v202, v73, s62, v203
	v_fma_f32 v212, v74, s62, v213
	v_fma_f32 v214, v75, s62, v215
	v_cndmask_b32_e64 v142, v204, v200, s[64:65]
	v_cndmask_b32_e64 v141, v204, v202, s[66:67]
	v_cndmask_b32_e64 v144, v204, v212, s[68:69]
	v_cndmask_b32_e64 v143, v204, v214, s[70:71]
	v_add_u32_e32 v72, s8, v128
	v_mad_i32_i24 v145, v72, s90, v118
	ds_read_b128 v[72:75], v145
	ds_read_b128 v[146:149], v145 offset:64
	ds_read_b128 v[224:227], v145 offset:128
	ds_read_b128 v[228:231], v145 offset:192
	ds_read_b32 v201, v220 offset:1116
	ds_read_b32 v203, v221 offset:1116
	ds_read_b32 v213, v222 offset:1116
	ds_read_b32 v215, v223 offset:1116
	s_waitcnt lgkmcnt(7)
	v_mfma_f32_16x16x32_bf16 v[72:75], v[72:75], v[24:27], 0
	s_waitcnt lgkmcnt(6)
	v_mfma_f32_16x16x32_bf16 v[72:75], v[146:149], v[28:31], v[72:75]
	s_waitcnt lgkmcnt(5)
	v_mfma_f32_16x16x32_bf16 v[72:75], v[224:227], v[32:35], v[72:75]
	s_waitcnt lgkmcnt(4)
	v_mfma_f32_16x16x32_bf16 v[72:75], v[228:231], v[36:39], v[72:75]
	s_nop 7
	s_waitcnt lgkmcnt(0)
	v_fma_f32 v200, v72, s62, v201
	v_fma_f32 v202, v73, s62, v203
	v_fma_f32 v212, v74, s62, v213
	v_fma_f32 v214, v75, s62, v215
	v_cndmask_b32_e64 v146, v204, v200, s[72:73]
	v_cndmask_b32_e64 v145, v204, v202, s[74:75]
	v_cndmask_b32_e64 v148, v204, v212, s[76:77]
	v_cndmask_b32_e64 v147, v204, v214, s[0:1]
	s_add_i32 s37, s41, 0x118
	v_add_u32_e32 v72, s37, v121
	v_mad_i32_i24 v149, v72, s90, v118
	ds_read_b128 v[72:75], v149
	ds_read_b128 v[150:153], v149 offset:64
	ds_read_b128 v[224:227], v149 offset:128
	ds_read_b128 v[228:231], v149 offset:192
	ds_read_b32 v201, v216 offset:1240
	ds_read_b32 v203, v217 offset:1240
	ds_read_b32 v213, v218 offset:1240
	ds_read_b32 v215, v219 offset:1240
	s_waitcnt lgkmcnt(7)
	v_mfma_f32_16x16x32_bf16 v[72:75], v[72:75], v[24:27], 0
	s_waitcnt lgkmcnt(6)
	v_mfma_f32_16x16x32_bf16 v[72:75], v[150:153], v[28:31], v[72:75]
	s_waitcnt lgkmcnt(5)
	v_mfma_f32_16x16x32_bf16 v[72:75], v[224:227], v[32:35], v[72:75]
	s_waitcnt lgkmcnt(4)
	v_mfma_f32_16x16x32_bf16 v[72:75], v[228:231], v[36:39], v[72:75]
	s_nop 7
	s_waitcnt lgkmcnt(0)
; #define LAS __attribute__((address_space(3)))
; template <int L>
; __device__ __forceinline__ void layer_body(const Args& args, LAS unsigned char* lds, const int wave, const int G, const int gw, const int NGW, const int lo, const int hi,
;                                            unsigned char* const ws_kernel, const XcdBarrier& bar, int& pid) {
;     ...
; #pragma unroll
;                     for (int t = 0; t < 16; ++t) {
;                         const int irow = (r0w - krlo + (t >> 1)) * 40 + coloff + 16 * (t & 1);
;                         const unsigned ka = IMG + (unsigned)((irow + qi) * KPITCH + 16 * kg);
;                         f32x4 a = (f32x4){0.f, 0.f, 0.f, 0.f};
; #pragma unroll
;                         for (int ks = 0; ks < 4; ++ks) a = __builtin_amdgcn_mfma_f32_16x16x32_bf16(*(const LAS bf16x8*)(size_t)(ka + 64 * ks), qfn[ks], a, 0, 0, 0);
;                         const int dr = r0w + (t >> 1) - r + 7;
; #pragma unroll
;                         for (int j = 0; j < 4; ++j) { const int kc = cs + 16 * (t & 1) + 4 * kg + j; const bool valid = (kc >= wsq) && (kc < wsq + 16); const int dc = min(max(kc - c + 15, 0), 30);
;                             sc[t][j] = valid ? a[j] * scale_log2 + rl[dr * 31 + dc] * LOG2E : -1e30f; }
;                         __builtin_amdgcn_sched_barrier(0);
;                     }
	v_fma_f32 v200, v72, s62, v201
	v_fma_f32 v202, v73, s62, v203
	v_fma_f32 v212, v74, s62, v213
	v_fma_f32 v214, v75, s62, v215
	v_cndmask_b32_e64 v150, v204, v200, s[64:65]
	v_cndmask_b32_e64 v149, v204, v202, s[66:67]
	v_cndmask_b32_e64 v152, v204, v212, s[68:69]
	v_cndmask_b32_e64 v151, v204, v214, s[70:71]
	v_add_u32_e32 v72, s37, v128
	v_mad_i32_i24 v153, v72, s90, v118
	ds_read_b128 v[72:75], v153
	ds_read_b128 v[154:157], v153 offset:64
	ds_read_b128 v[224:227], v153 offset:128
	ds_read_b128 v[228:231], v153 offset:192
	ds_read_b32 v201, v220 offset:1240
	ds_read_b32 v203, v221 offset:1240
	ds_read_b32 v213, v222 offset:1240
	ds_read_b32 v215, v223 offset:1240
	s_waitcnt lgkmcnt(7)
	v_mfma_f32_16x16x32_bf16 v[72:75], v[72:75], v[24:27], 0
	s_waitcnt lgkmcnt(6)
	v_mfma_f32_16x16x32_bf16 v[72:75], v[154:157], v[28:31], v[72:75]
	s_waitcnt lgkmcnt(5)
	v_mfma_f32_16x16x32_bf16 v[72:75], v[224:227], v[32:35], v[72:75]
	s_waitcnt lgkmcnt(4)
	v_mfma_f32_16x16x32_bf16 v[72:75], v[228:231], v[36:39], v[72:75]
	s_nop 7
	s_waitcnt lgkmcnt(0)
	v_fma_f32 v200, v72, s62, v201
	v_fma_f32 v202, v73, s62, v203
	v_fma_f32 v212, v74, s62, v213
	v_fma_f32 v214, v75, s62, v215
	v_cndmask_b32_e64 v154, v204, v200, s[72:73]
	v_cndmask_b32_e64 v153, v204, v202, s[74:75]
	v_cndmask_b32_e64 v156, v204, v212, s[76:77]
	v_cndmask_b32_e64 v155, v204, v214, s[0:1]
	s_add_i32 s38, s41, 0x140
	v_add_u32_e32 v72, s38, v121
	v_mad_i32_i24 v157, v72, s90, v118
	ds_read_b128 v[72:75], v157
	ds_read_b128 v[158:161], v157 offset:64
	ds_read_b128 v[224:227], v157 offset:128
	ds_read_b128 v[228:231], v157 offset:192
	ds_read_b32 v201, v216 offset:1364
	ds_read_b32 v203, v217 offset:1364
	ds_read_b32 v213, v218 offset:1364
	ds_read_b32 v215, v219 offset:1364
	s_waitcnt lgkmcnt(7)
	v_mfma_f32_16x16x32_bf16 v[72:75], v[72:75], v[24:27], 0
	s_waitcnt lgkmcnt(6)
	v_mfma_f32_16x16x32_bf16 v[72:75], v[158:161], v[28:31], v[72:75]
	s_waitcnt lgkmcnt(5)
	v_mfma_f32_16x16x32_bf16 v[72:75], v[224:227], v[32:35], v[72:75]
	s_waitcnt lgkmcnt(4)
	v_mfma_f32_16x16x32_bf16 v[72:75], v[228:231], v[36:39], v[72:75]
	s_nop 7
	s_waitcnt lgkmcnt(0)
	v_fma_f32 v200, v72, s62, v201
	v_fma_f32 v202, v73, s62, v203
	v_fma_f32 v212, v74, s62, v213
	v_fma_f32 v214, v75, s62, v215
	v_cndmask_b32_e64 v158, v204, v200, s[64:65]
	v_cndmask_b32_e64 v157, v204, v202, s[66:67]
	v_cndmask_b32_e64 v160, v204, v212, s[68:69]
	v_cndmask_b32_e64 v159, v204, v214, s[70:71]
	v_add_u32_e32 v72, s38, v128
	v_mad_i32_i24 v161, v72, s90, v118
	ds_read_b128 v[72:75], v161
	ds_read_b128 v[162:165], v161 offset:64
	ds_read_b128 v[224:227], v161 offset:128
	ds_read_b128 v[228:231], v161 offset:192
	ds_read_b32 v201, v220 offset:1364
	ds_read_b32 v203, v221 offset:1364
	ds_read_b32 v213, v222 offset:1364
	ds_read_b32 v215, v223 offset:1364
	s_waitcnt lgkmcnt(7)
	v_mfma_f32_16x16x32_bf16 v[72:75], v[72:75], v[24:27], 0
	s_waitcnt lgkmcnt(6)
	v_mfma_f32_16x16x32_bf16 v[72:75], v[162:165], v[28:31], v[72:75]
	s_waitcnt lgkmcnt(5)
	v_mfma_f32_16x16x32_bf16 v[72:75], v[224:227], v[32:35], v[72:75]
	s_waitcnt lgkmcnt(4)
	v_mfma_f32_16x16x32_bf16 v[72:75], v[228:231], v[36:39], v[72:75]
	s_nop 7
	s_waitcnt lgkmcnt(0)
	v_fma_f32 v200, v72, s62, v201
	v_fma_f32 v202, v73, s62, v203
	v_fma_f32 v212, v74, s62, v213
	v_fma_f32 v214, v75, s62, v215
	v_cndmask_b32_e64 v162, v204, v200, s[72:73]
	v_cndmask_b32_e64 v161, v204, v202, s[74:75]
	v_cndmask_b32_e64 v164, v204, v212, s[76:77]
	v_cndmask_b32_e64 v163, v204, v214, s[0:1]
	s_add_i32 s39, s41, 0x168
	v_add_u32_e32 v72, s39, v121
	v_mad_i32_i24 v165, v72, s90, v118
	ds_read_b128 v[72:75], v165
	ds_read_b128 v[166:169], v165 offset:64
	ds_read_b128 v[224:227], v165 offset:128
	ds_read_b128 v[228:231], v165 offset:192
	ds_read_b32 v201, v216 offset:1488
	ds_read_b32 v203, v217 offset:1488
	ds_read_b32 v213, v218 offset:1488
	ds_read_b32 v215, v219 offset:1488
	s_waitcnt lgkmcnt(7)
	v_mfma_f32_16x16x32_bf16 v[72:75], v[72:75], v[24:27], 0
	s_waitcnt lgkmcnt(6)
	v_mfma_f32_16x16x32_bf16 v[72:75], v[166:169], v[28:31], v[72:75]
	s_waitcnt lgkmcnt(5)
	v_mfma_f32_16x16x32_bf16 v[72:75], v[224:227], v[32:35], v[72:75]
	s_waitcnt lgkmcnt(4)
	v_mfma_f32_16x16x32_bf16 v[72:75], v[228:231], v[36:39], v[72:75]
	s_nop 7
	s_waitcnt lgkmcnt(0)
	v_fma_f32 v200, v72, s62, v201
	v_fma_f32 v202, v73, s62, v203
	v_fma_f32 v212, v74, s62, v213
	v_fma_f32 v214, v75, s62, v215
	v_cndmask_b32_e64 v166, v204, v200, s[64:65]
	v_cndmask_b32_e64 v165, v204, v202, s[66:67]
	v_cndmask_b32_e64 v168, v204, v212, s[68:69]
	v_cndmask_b32_e64 v167, v204, v214, s[70:71]
	v_add_u32_e32 v72, s39, v128
	v_mad_i32_i24 v169, v72, s90, v118
	ds_read_b128 v[72:75], v169
	ds_read_b128 v[170:173], v169 offset:64
	ds_read_b128 v[224:227], v169 offset:128
	ds_read_b128 v[228:231], v169 offset:192
	ds_read_b32 v201, v220 offset:1488
	ds_read_b32 v203, v221 offset:1488
	ds_read_b32 v213, v222 offset:1488
	ds_read_b32 v215, v223 offset:1488
	s_waitcnt lgkmcnt(7)
	v_mfma_f32_16x16x32_bf16 v[72:75], v[72:75], v[24:27], 0
	s_waitcnt lgkmcnt(6)
	v_mfma_f32_16x16x32_bf16 v[72:75], v[170:173], v[28:31], v[72:75]
	s_waitcnt lgkmcnt(5)
	v_mfma_f32_16x16x32_bf16 v[72:75], v[224:227], v[32:35], v[72:75]
	s_waitcnt lgkmcnt(4)
	v_mfma_f32_16x16x32_bf16 v[72:75], v[228:231], v[36:39], v[72:75]
	s_nop 7
	s_waitcnt lgkmcnt(0)
; #define LAS __attribute__((address_space(3)))
; template <int L>
; __device__ __forceinline__ void layer_body(const Args& args, LAS unsigned char* lds, const int wave, const int G, const int gw, const int NGW, const int lo, const int hi,
;                                            unsigned char* const ws_kernel, const XcdBarrier& bar, int& pid) {
;     ...
; #pragma unroll
;                     for (int t = 0; t < 16; ++t) {
;                         const int irow = (r0w - krlo + (t >> 1)) * 40 + coloff + 16 * (t & 1);
;                         const unsigned ka = IMG + (unsigned)((irow + qi) * KPITCH + 16 * kg);
;                         f32x4 a = (f32x4){0.f, 0.f, 0.f, 0.f};
; #pragma unroll
;                         for (int ks = 0; ks < 4; ++ks) a = __builtin_amdgcn_mfma_f32_16x16x32_bf16(*(const LAS bf16x8*)(size_t)(ka + 64 * ks), qfn[ks], a, 0, 0, 0);
;                         const int dr = r0w + (t >> 1) - r + 7;
; #pragma unroll
;                         for (int j = 0; j < 4; ++j) { const int kc = cs + 16 * (t & 1) + 4 * kg + j; const bool valid = (kc >= wsq) && (kc < wsq + 16); const int dc = min(max(kc - c + 15, 0), 30);
;                             sc[t][j] = valid ? a[j] * scale_log2 + rl[dr * 31 + dc] * LOG2E : -1e30f; }
;                         __builtin_amdgcn_sched_barrier(0);
;                     }
;                     float mx = -1e30f;
; #pragma unroll
;                     for (int t = 0; t < 16; ++t)
; #pragma unroll
;                         for (int j = 0; j < 4; ++j) mx = fmaxf(mx, sc[t][j]);
;                     mx = fmaxf(mx, __shfl_xor(mx, 16)); mx = fmaxf(mx, __shfl_xor(mx, 32));
	v_fma_f32 v200, v72, s62, v201
	v_fma_f32 v202, v73, s62, v203
	v_fma_f32 v212, v74, s62, v213
	v_fma_f32 v214, v75, s62, v215
	v_cndmask_b32_e64 v170, v204, v200, s[72:73]
	v_cndmask_b32_e64 v169, v204, v202, s[74:75]
	v_cndmask_b32_e64 v172, v204, v212, s[76:77]
	v_cndmask_b32_e64 v171, v204, v214, s[0:1]
	s_add_i32 s40, s41, 0x190
	v_add_u32_e32 v72, s40, v121
	v_mad_i32_i24 v173, v72, s90, v118
	ds_read_b128 v[72:75], v173
	ds_read_b128 v[174:177], v173 offset:64
	ds_read_b128 v[224:227], v173 offset:128
	ds_read_b128 v[228:231], v173 offset:192
	ds_read_b32 v201, v216 offset:1612
	ds_read_b32 v203, v217 offset:1612
	ds_read_b32 v213, v218 offset:1612
	ds_read_b32 v215, v219 offset:1612
	s_waitcnt lgkmcnt(7)
	v_mfma_f32_16x16x32_bf16 v[72:75], v[72:75], v[24:27], 0
	s_waitcnt lgkmcnt(6)
	v_mfma_f32_16x16x32_bf16 v[72:75], v[174:177], v[28:31], v[72:75]
	s_waitcnt lgkmcnt(5)
	v_mfma_f32_16x16x32_bf16 v[72:75], v[224:227], v[32:35], v[72:75]
	s_waitcnt lgkmcnt(4)
	v_mfma_f32_16x16x32_bf16 v[72:75], v[228:231], v[36:39], v[72:75]
	s_nop 7
	s_waitcnt lgkmcnt(0)
	v_fma_f32 v200, v72, s62, v201
	v_fma_f32 v202, v73, s62, v203
	v_fma_f32 v212, v74, s62, v213
	v_fma_f32 v214, v75, s62, v215
	v_cndmask_b32_e64 v174, v204, v200, s[64:65]
	v_cndmask_b32_e64 v173, v204, v202, s[66:67]
	v_cndmask_b32_e64 v176, v204, v212, s[68:69]
	v_cndmask_b32_e64 v175, v204, v214, s[70:71]
	v_add_u32_e32 v72, s40, v128
	v_mad_i32_i24 v177, v72, s90, v118
	ds_read_b128 v[72:75], v177
	ds_read_b128 v[178:181], v177 offset:64
	ds_read_b128 v[224:227], v177 offset:128
	ds_read_b128 v[228:231], v177 offset:192
	ds_read_b32 v201, v220 offset:1612
	ds_read_b32 v203, v221 offset:1612
	ds_read_b32 v213, v222 offset:1612
	ds_read_b32 v215, v223 offset:1612
	s_waitcnt lgkmcnt(7)
	v_mfma_f32_16x16x32_bf16 v[72:75], v[72:75], v[24:27], 0
	s_waitcnt lgkmcnt(6)
	v_mfma_f32_16x16x32_bf16 v[72:75], v[178:181], v[28:31], v[72:75]
	s_waitcnt lgkmcnt(5)
	v_mfma_f32_16x16x32_bf16 v[72:75], v[224:227], v[32:35], v[72:75]
	s_waitcnt lgkmcnt(4)
	v_mfma_f32_16x16x32_bf16 v[72:75], v[228:231], v[36:39], v[72:75]
	s_nop 7
	s_waitcnt lgkmcnt(0)
	v_fma_f32 v200, v72, s62, v201
	v_fma_f32 v202, v73, s62, v203
	v_fma_f32 v212, v74, s62, v213
	v_fma_f32 v214, v75, s62, v215
	v_cndmask_b32_e64 v178, v204, v200, s[72:73]
	v_cndmask_b32_e64 v177, v204, v202, s[74:75]
	v_cndmask_b32_e64 v191, v204, v212, s[76:77]
	v_cndmask_b32_e64 v188, v204, v214, s[0:1]
	s_addk_i32 s41, 0x1b8
	v_add_u32_e32 v72, s41, v121
	v_mad_i32_i24 v121, v72, s90, v118
	ds_read_b128 v[72:75], v121
	ds_read_b128 v[180:183], v121 offset:64
	ds_read_b128 v[224:227], v121 offset:128
	ds_read_b128 v[228:231], v121 offset:192
	ds_read_b32 v201, v216 offset:1736
	ds_read_b32 v203, v217 offset:1736
	ds_read_b32 v213, v218 offset:1736
	ds_read_b32 v215, v219 offset:1736
	s_waitcnt lgkmcnt(7)
	v_mfma_f32_16x16x32_bf16 v[72:75], v[72:75], v[24:27], 0
	s_waitcnt lgkmcnt(6)
	v_mfma_f32_16x16x32_bf16 v[72:75], v[180:183], v[28:31], v[72:75]
	s_waitcnt lgkmcnt(5)
	v_mfma_f32_16x16x32_bf16 v[72:75], v[224:227], v[32:35], v[72:75]
	s_waitcnt lgkmcnt(4)
	v_mfma_f32_16x16x32_bf16 v[72:75], v[228:231], v[36:39], v[72:75]
	s_nop 7
	s_waitcnt lgkmcnt(0)
	v_fma_f32 v200, v72, s62, v201
	v_fma_f32 v202, v73, s62, v203
	v_fma_f32 v212, v74, s62, v213
	v_fma_f32 v214, v75, s62, v215
	v_cndmask_b32_e64 v205, v204, v200, s[64:65]
	v_cndmask_b32_e64 v121, v204, v202, s[66:67]
	v_cndmask_b32_e64 v207, v204, v212, s[68:69]
	v_cndmask_b32_e64 v206, v204, v214, s[70:71]
	v_add_u32_e32 v72, s41, v128
	v_mad_i32_i24 v118, v72, s90, v118
	ds_read_b128 v[72:75], v118
	ds_read_b128 v[124:127], v118 offset:64
	ds_read_b128 v[224:227], v118 offset:128
	ds_read_b128 v[228:231], v118 offset:192
	ds_read_b32 v201, v220 offset:1736
	ds_read_b32 v203, v221 offset:1736
	ds_read_b32 v213, v222 offset:1736
	ds_read_b32 v215, v223 offset:1736
	s_waitcnt lgkmcnt(7)
	v_mfma_f32_16x16x32_bf16 v[72:75], v[72:75], v[24:27], 0
	s_waitcnt lgkmcnt(6)
	v_mfma_f32_16x16x32_bf16 v[72:75], v[124:127], v[28:31], v[72:75]
	s_waitcnt lgkmcnt(5)
	v_mfma_f32_16x16x32_bf16 v[72:75], v[224:227], v[32:35], v[72:75]
	s_waitcnt lgkmcnt(4)
	v_mfma_f32_16x16x32_bf16 v[72:75], v[228:231], v[36:39], v[72:75]
	s_nop 7
	s_waitcnt lgkmcnt(0)
	v_fma_f32 v200, v72, s62, v201
	v_fma_f32 v202, v73, s62, v203
	v_fma_f32 v212, v74, s62, v213
	v_fma_f32 v214, v75, s62, v215
	v_cndmask_b32_e64 v209, v204, v200, s[72:73]
	v_cndmask_b32_e64 v208, v204, v202, s[74:75]
	v_cndmask_b32_e64 v211, v204, v212, s[76:77]
	v_cndmask_b32_e64 v210, v204, v214, s[0:1]
	s_lshl_b32 s36, s36, 7
	s_mov_b32 s0, 0xf149f2ca
	v_max3_f32 v72, v115, s0, v104
	v_max3_f32 v72, v72, v117, v116
	v_max3_f32 v72, v72, v120, v119
	v_max3_f32 v72, v72, v123, v122
	v_max3_f32 v72, v72, v131, v129
	v_max3_f32 v72, v72, v136, v135
	v_max3_f32 v72, v72, v138, v137
	v_max3_f32 v72, v72, v140, v139
	v_max3_f32 v72, v72, v142, v141
	v_max3_f32 v72, v72, v144, v143
	v_max3_f32 v72, v72, v146, v145
	v_max3_f32 v72, v72, v148, v147
	v_max3_f32 v72, v72, v150, v149
	v_max3_f32 v72, v72, v152, v151
	v_max3_f32 v72, v72, v154, v153
	v_max3_f32 v72, v72, v156, v155
	v_max3_f32 v72, v72, v158, v157
	v_max3_f32 v72, v72, v160, v159
	v_max3_f32 v72, v72, v162, v161
	v_max3_f32 v72, v72, v164, v163
	v_max3_f32 v72, v72, v166, v165
	v_max3_f32 v72, v72, v168, v167
	v_max3_f32 v72, v72, v170, v169
	v_max3_f32 v72, v72, v172, v171
	v_max3_f32 v72, v72, v174, v173
	v_max3_f32 v72, v72, v176, v175
	v_max3_f32 v72, v72, v178, v177
	v_max3_f32 v72, v72, v191, v188
	v_and_b32_e32 v74, 64, v107
	v_max3_f32 v72, v72, v205, v121
	v_xor_b32_e32 v73, 16, v107
	v_add_u32_e32 v74, 64, v74
	v_max3_f32 v72, v72, v207, v206
	v_cmp_lt_i32_e32 vcc, v73, v74
	v_max3_f32 v72, v72, v209, v208
	v_max3_f32 v72, v72, v211, v210
	v_cndmask_b32_e32 v73, v107, v73, vcc
	v_lshlrev_b32_e32 v212, 2, v73
	ds_bpermute_b32 v73, v212, v72
	s_waitcnt lgkmcnt(0)
	s_barrier
; template <int L>
; __device__ __forceinline__ void layer_body(const Args& args, LAS unsigned char* lds, const int wave, const int G, const int gw, const int NGW, const int lo, const int hi,
;                                            unsigned char* const ws_kernel, const XcdBarrier& bar, int& pid) {
;     ...
;                     mx = fmaxf(mx, __shfl_xor(mx, 16)); mx = fmaxf(mx, __shfl_xor(mx, 32));
;                     float sum = 0.f;
; #pragma unroll
;                     for (int t = 0; t < 16; ++t)
; #pragma unroll
;                         for (int j = 0; j < 4; ++j) { sc[t][j] = __builtin_amdgcn_exp2f(sc[t][j] - mx); sum += sc[t][j]; }
;                     sum += __shfl_xor(sum, 16); sum += __shfl_xor(sum, 32);
	s_add_i32 s21, s21, s86
	v_max_f32_e32 v73, v73, v73
	v_max_f32_e32 v72, v72, v73
	v_xor_b32_e32 v73, 32, v107
	v_cmp_lt_i32_e32 vcc, v73, v74
	s_cmp_ge_i32 s21, s52
	s_cselect_b64 s[0:1], -1, 0
	v_cndmask_b32_e32 v73, v107, v73, vcc
	v_lshlrev_b32_e32 v213, 2, v73
	ds_bpermute_b32 v73, v213, v72
	s_and_b64 vcc, exec, s[0:1]
	s_waitcnt lgkmcnt(0)
	v_max_f32_e32 v73, v73, v73
	v_max_f32_e32 v214, v72, v73
	v_sub_f32_e32 v72, v115, v214
	v_exp_f32_e32 v192, v72
	v_sub_f32_e32 v72, v104, v214
	v_exp_f32_e32 v200, v72
	v_sub_f32_e32 v72, v117, v214
	v_exp_f32_e32 v196, v72
	v_sub_f32_e32 v72, v116, v214
	v_exp_f32_e32 v202, v72
	v_sub_f32_e32 v72, v120, v214
	v_sub_f32_e32 v104, v208, v214
	v_exp_f32_e32 v198, v72
	v_sub_f32_e32 v72, v119, v214
	v_exp_f32_e32 v119, v104
	v_sub_f32_e32 v104, v211, v214
	v_exp_f32_e32 v116, v104
	v_sub_f32_e32 v104, v210, v214
	v_sub_f32_e32 v73, v121, v214
	v_exp_f32_e32 v121, v104
	v_add_f32_e32 v104, 0, v192
	v_exp_f32_e32 v203, v72
	v_sub_f32_e32 v72, v123, v214
	v_add_f32_e32 v104, v200, v104
	v_exp_f32_e32 v201, v72
	v_sub_f32_e32 v72, v122, v214
	v_add_f32_e32 v104, v196, v104
	v_exp_f32_e32 v204, v72
	v_sub_f32_e32 v72, v131, v214
	v_add_f32_e32 v104, v202, v104
	v_exp_f32_e32 v182, v72
	v_sub_f32_e32 v72, v129, v214
	v_add_f32_e32 v104, v198, v104
	v_exp_f32_e32 v193, v72
	v_sub_f32_e32 v72, v136, v214
	v_add_f32_e32 v104, v203, v104
	v_exp_f32_e32 v186, v72
	v_sub_f32_e32 v72, v135, v214
	v_add_f32_e32 v104, v201, v104
	v_exp_f32_e32 v195, v72
	v_sub_f32_e32 v72, v138, v214
	v_add_f32_e32 v104, v204, v104
	v_exp_f32_e32 v189, v72
	v_sub_f32_e32 v72, v137, v214
	v_add_f32_e32 v104, v182, v104
	v_exp_f32_e32 v197, v72
	v_sub_f32_e32 v72, v140, v214
	v_add_f32_e32 v104, v193, v104
	v_exp_f32_e32 v194, v72
	v_sub_f32_e32 v72, v139, v214
	v_add_f32_e32 v104, v186, v104
	v_exp_f32_e32 v199, v72
	v_sub_f32_e32 v72, v142, v214
	v_add_f32_e32 v104, v195, v104
	v_exp_f32_e32 v179, v72
	v_sub_f32_e32 v72, v141, v214
	v_add_f32_e32 v104, v189, v104
	v_exp_f32_e32 v183, v72
	v_sub_f32_e32 v72, v144, v214
	v_add_f32_e32 v104, v197, v104
	v_exp_f32_e32 v180, v72
	v_sub_f32_e32 v72, v143, v214
	v_add_f32_e32 v104, v194, v104
	v_exp_f32_e32 v185, v72
	v_sub_f32_e32 v72, v146, v214
	v_add_f32_e32 v104, v199, v104
	v_exp_f32_e32 v181, v72
	v_sub_f32_e32 v72, v145, v214
	v_add_f32_e32 v104, v179, v104
	v_exp_f32_e32 v187, v72
	v_sub_f32_e32 v72, v148, v214
	v_add_f32_e32 v104, v183, v104
	v_exp_f32_e32 v184, v72
	v_sub_f32_e32 v72, v147, v214
	v_add_f32_e32 v104, v180, v104
	v_exp_f32_e32 v190, v72
	v_sub_f32_e32 v72, v150, v214
	v_add_f32_e32 v104, v185, v104
	v_exp_f32_e32 v138, v72
	v_sub_f32_e32 v72, v149, v214
	v_add_f32_e32 v104, v181, v104
	v_exp_f32_e32 v146, v72
	v_sub_f32_e32 v72, v152, v214
	v_add_f32_e32 v104, v187, v104
	v_exp_f32_e32 v142, v72
	v_sub_f32_e32 v72, v151, v214
	v_add_f32_e32 v104, v184, v104
	v_exp_f32_e32 v148, v72
	v_sub_f32_e32 v72, v154, v214
	v_add_f32_e32 v104, v190, v104
	v_exp_f32_e32 v144, v72
	v_sub_f32_e32 v72, v153, v214
	v_add_f32_e32 v104, v138, v104
	v_exp_f32_e32 v150, v72
	v_sub_f32_e32 v72, v156, v214
	v_add_f32_e32 v104, v146, v104
	v_exp_f32_e32 v147, v72
	v_sub_f32_e32 v72, v155, v214
	v_add_f32_e32 v104, v142, v104
	v_exp_f32_e32 v152, v72
	v_sub_f32_e32 v72, v158, v214
	v_add_f32_e32 v104, v148, v104
	v_exp_f32_e32 v130, v72
	v_sub_f32_e32 v72, v157, v214
	v_add_f32_e32 v104, v144, v104
	v_exp_f32_e32 v139, v72
	v_sub_f32_e32 v72, v160, v214
	v_add_f32_e32 v104, v150, v104
	v_exp_f32_e32 v134, v72
	v_sub_f32_e32 v72, v159, v214
	v_add_f32_e32 v104, v147, v104
	v_exp_f32_e32 v141, v72
	v_sub_f32_e32 v72, v162, v214
	v_add_f32_e32 v104, v152, v104
	v_exp_f32_e32 v136, v72
	v_sub_f32_e32 v72, v161, v214
	v_add_f32_e32 v104, v130, v104
	v_exp_f32_e32 v143, v72
	v_sub_f32_e32 v72, v164, v214
	v_add_f32_e32 v104, v139, v104
	v_exp_f32_e32 v140, v72
	v_sub_f32_e32 v72, v163, v214
	v_add_f32_e32 v104, v134, v104
	v_exp_f32_e32 v145, v72
	v_sub_f32_e32 v72, v166, v214
	v_add_f32_e32 v104, v141, v104
	v_exp_f32_e32 v122, v72
	v_sub_f32_e32 v72, v165, v214
	v_add_f32_e32 v104, v136, v104
	v_exp_f32_e32 v131, v72
	v_sub_f32_e32 v72, v168, v214
	v_add_f32_e32 v104, v143, v104
	v_exp_f32_e32 v126, v72
	v_sub_f32_e32 v72, v167, v214
	v_add_f32_e32 v104, v140, v104
	v_exp_f32_e32 v133, v72
	v_sub_f32_e32 v72, v170, v214
	v_add_f32_e32 v104, v145, v104
	v_exp_f32_e32 v128, v72
	v_sub_f32_e32 v72, v169, v214
	v_add_f32_e32 v104, v122, v104
	v_exp_f32_e32 v135, v72
	v_sub_f32_e32 v72, v172, v214
	v_add_f32_e32 v104, v131, v104
	v_exp_f32_e32 v132, v72
	v_sub_f32_e32 v72, v171, v214
	v_add_f32_e32 v104, v126, v104
	v_exp_f32_e32 v137, v72
	v_sub_f32_e32 v72, v174, v214
	v_add_f32_e32 v104, v133, v104
	v_exp_f32_e32 v75, v72
	v_sub_f32_e32 v72, v173, v214
	v_add_f32_e32 v104, v128, v104
	v_exp_f32_e32 v123, v72
	v_sub_f32_e32 v72, v176, v214
	v_add_f32_e32 v104, v135, v104
	v_exp_f32_e32 v118, v72
	v_sub_f32_e32 v72, v175, v214
	v_add_f32_e32 v104, v132, v104
	v_exp_f32_e32 v125, v72
	v_sub_f32_e32 v72, v178, v214
	v_add_f32_e32 v104, v137, v104
	v_exp_f32_e32 v120, v72
	v_sub_f32_e32 v72, v177, v214
	v_add_f32_e32 v104, v75, v104
	v_exp_f32_e32 v127, v72
	v_sub_f32_e32 v72, v191, v214
	v_add_f32_e32 v104, v123, v104
	v_exp_f32_e32 v124, v72
	v_sub_f32_e32 v72, v188, v214
	v_add_f32_e32 v104, v118, v104
	v_exp_f32_e32 v129, v72
	v_sub_f32_e32 v72, v205, v214
	v_add_f32_e32 v104, v125, v104
	v_exp_f32_e32 v72, v72
	v_add_f32_e32 v104, v120, v104
	v_exp_f32_e32 v115, v73
	v_sub_f32_e32 v73, v207, v214
	v_add_f32_e32 v104, v127, v104
	v_exp_f32_e32 v73, v73
	v_sub_f32_e32 v74, v206, v214
	v_add_f32_e32 v104, v124, v104
	v_exp_f32_e32 v117, v74
	v_sub_f32_e32 v74, v209, v214
	v_add_f32_e32 v104, v129, v104
	v_exp_f32_e32 v74, v74
	v_add_f32_e32 v104, v72, v104
	v_add_f32_e32 v104, v115, v104
	v_add_f32_e32 v104, v73, v104
	v_add_f32_e32 v104, v117, v104
	v_add_f32_e32 v104, v74, v104
	v_add_f32_e32 v104, v119, v104
	v_add_f32_e32 v104, v116, v104
	v_add_f32_e32 v104, v121, v104
	ds_bpermute_b32 v149, v212, v104
	v_lshlrev_b32_e32 v153, 2, v77
	v_and_b32_e32 v153, 12, v153
	s_waitcnt lgkmcnt(0)
; #define LAS __attribute__((address_space(3)))
; template <int L>
; __device__ __forceinline__ void layer_body(const Args& args, LAS unsigned char* lds, const int wave, const int G, const int gw, const int NGW, const int lo, const int hi,
;                                            unsigned char* const ws_kernel, const XcdBarrier& bar, int& pid) {
;     ...
;                     __syncthreads();
; #pragma unroll
;                     for (int i = 0; i < 14; ++i) { const int kid = skey + 32 * i; *(LAS v4u*)(size_t)(IMG + vimg_off(kid, sch)) = rst[i]; }
;                     __syncthreads();
;                     if (unit + GH < UEND) { NA_LOADROWS(unit + GH, rst, D); NA_LOADQ(unit + GH); }
	v_add_f32_e32 v149, v104, v149
	v_lshlrev_b32_e32 v104, 8, v77
	v_bfe_u32 v77, v77, 2, 2
	v_bitop3_b32 v77, v153, v112, v77 bitop3:0x36
	v_lshlrev_b32_e32 v77, 4, v77
	v_add3_u32 v77, v104, 0, v77
	ds_bpermute_b32 v151, v213, v149
	v_add_u32_e32 v104, 0x10000, v77
	s_waitcnt vmcnt(13)
	ds_write_b128 v77, v[0:3]
	s_waitcnt vmcnt(12)
	ds_write_b128 v77, v[4:7] offset:8192
	s_waitcnt vmcnt(11)
	ds_write_b128 v77, v[8:11] offset:16384
	s_waitcnt vmcnt(10)
	ds_write_b128 v77, v[12:15] offset:24576
	s_waitcnt vmcnt(9)
	ds_write_b128 v77, v[16:19] offset:32768
	s_waitcnt vmcnt(8)
	ds_write_b128 v77, v[20:23] offset:40960
	s_waitcnt vmcnt(7)
	ds_write_b128 v77, v[40:43] offset:49152
	s_waitcnt vmcnt(6)
	ds_write_b128 v77, v[44:47] offset:57344
	s_waitcnt vmcnt(5)
	ds_write_b128 v104, v[48:51]
	v_add_u32_e32 v104, 0x12000, v77
	s_waitcnt vmcnt(4)
	ds_write_b128 v104, v[52:55]
	v_add_u32_e32 v104, 0x14000, v77
	s_waitcnt vmcnt(3)
	ds_write_b128 v104, v[56:59]
	v_add_u32_e32 v104, 0x16000, v77
	s_waitcnt vmcnt(2)
	ds_write_b128 v104, v[60:63]
	v_add_u32_e32 v104, 0x18000, v77
	v_add_u32_e32 v77, 0x1a000, v77
	s_waitcnt vmcnt(1)
	ds_write_b128 v104, v[64:67]
	s_waitcnt vmcnt(0)
	ds_write_b128 v77, v[68:71]
	s_waitcnt lgkmcnt(0)
	s_barrier
	s_cbranch_vccnz .LBB0_843
	s_add_i32 s42, s83, s84
	s_and_b32 s45, s42, 28
	s_add_i32 s47, s91, s96
	v_sub_u32_e64 v1, s45, 1 clamp
	s_and_b32 s42, s47, 0x780
	v_lshlrev_b32_e32 v0, 3, v112
	s_and_b32 s44, s21, 1
	s_max_u32 s46, s45, 4
	v_min_u32_e32 v1, 24, v1
	s_lshl_b32 s48, s42, 1
	s_add_u32 s42, s59, s48
	v_lshlrev_b32_e32 v104, 1, v0
	v_subrev_u32_e32 v0, s46, v1
	s_addc_u32 s43, s80, 0
	v_add_u32_e32 v31, 11, v0
	v_sub_u32_e64 v30, s45, 4 clamp
	v_lshl_add_u64 v[24:25], s[42:43], 0, v[104:105]
	s_and_b32 s46, s47, 0xfffff800
	s_mul_i32 s42, s44, 24
	v_min_i32_e32 v0, v78, v31
	v_min_i32_e32 v2, v80, v31
	v_min_i32_e32 v8, v82, v31
	v_min_i32_e32 v10, v84, v31
	v_min_i32_e32 v16, v86, v31
	v_min_i32_e32 v18, v88, v31
	v_min_i32_e32 v26, v90, v31
	v_min_i32_e32 v28, v92, v31
	s_or_b32 s47, s46, s42
	v_add_lshl_u32 v0, v0, v30, 6
	v_add_lshl_u32 v2, v2, v30, 6
	v_add_lshl_u32 v8, v8, v30, 6
	v_add_lshl_u32 v10, v10, v30, 6
	v_add_lshl_u32 v16, v16, v30, 6
	v_add_lshl_u32 v18, v18, v30, 6
	v_add_lshl_u32 v26, v26, v30, 6
	v_add_lshl_u32 v28, v28, v30, 6
	v_add3_u32 v0, v79, s47, v0
	v_add3_u32 v2, v81, s47, v2
	v_add3_u32 v8, v83, s47, v8
	v_add3_u32 v10, v85, s47, v10
	v_add3_u32 v16, v87, s47, v16
	v_add3_u32 v18, v89, s47, v18
	v_add3_u32 v26, v91, s47, v26
	v_add3_u32 v28, v93, s47, v28
	v_mad_i64_i32 v[0:1], s[42:43], v0, s22, v[24:25]
	v_mad_i64_i32 v[4:5], s[42:43], v2, s22, v[24:25]
	v_mad_i64_i32 v[8:9], s[42:43], v8, s22, v[24:25]
	v_mad_i64_i32 v[12:13], s[42:43], v10, s22, v[24:25]
	v_mad_i64_i32 v[16:17], s[42:43], v16, s22, v[24:25]
	v_mad_i64_i32 v[20:21], s[42:43], v18, s22, v[24:25]
	v_mad_i64_i32 v[26:27], s[42:43], v26, s22, v[24:25]
	v_mad_i64_i32 v[28:29], s[42:43], v28, s22, v[24:25]
	global_load_dwordx4 v[0:3], v[0:1], off
	s_nop 0
	global_load_dwordx4 v[4:7], v[4:5], off
	s_nop 0
	global_load_dwordx4 v[8:11], v[8:9], off
	s_nop 0
	global_load_dwordx4 v[12:15], v[12:13], off
	s_nop 0
	global_load_dwordx4 v[16:19], v[16:17], off
	s_nop 0
	global_load_dwordx4 v[20:23], v[20:21], off
	s_nop 0
	global_load_dwordx4 v[40:43], v[26:27], off
	global_load_dwordx4 v[44:47], v[28:29], off
	v_min_i32_e32 v26, v94, v31
	v_min_i32_e32 v28, v96, v31
	v_add_lshl_u32 v26, v26, v30, 6
	v_add_lshl_u32 v28, v28, v30, 6
	v_add3_u32 v26, v95, s47, v26
	v_add3_u32 v28, v97, s47, v28
	v_mad_i64_i32 v[26:27], s[42:43], v26, s22, v[24:25]
	v_mad_i64_i32 v[28:29], s[42:43], v28, s22, v[24:25]
	global_load_dwordx4 v[48:51], v[26:27], off
	global_load_dwordx4 v[52:55], v[28:29], off
	v_min_i32_e32 v26, v98, v31
	v_min_i32_e32 v28, v100, v31
	v_add_lshl_u32 v26, v26, v30, 6
	v_add_lshl_u32 v28, v28, v30, 6
	v_add3_u32 v26, v99, s47, v26
	v_add3_u32 v28, v101, s47, v28
	v_mad_i64_i32 v[26:27], s[42:43], v26, s22, v[24:25]
	v_mad_i64_i32 v[28:29], s[42:43], v28, s22, v[24:25]
	global_load_dwordx4 v[56:59], v[26:27], off
	global_load_dwordx4 v[60:63], v[28:29], off
	v_min_i32_e32 v26, v102, v31
	v_min_i32_e32 v28, v113, v31
	v_add_lshl_u32 v26, v26, v30, 6
	v_add_lshl_u32 v28, v28, v30, 6
	v_add3_u32 v26, v103, s47, v26
	v_add3_u32 v28, v114, s47, v28
	v_mad_i64_i32 v[26:27], s[42:43], v26, s22, v[24:25]
	v_mad_i64_i32 v[24:25], s[42:43], v28, s22, v[24:25]
	s_add_u32 s42, s55, s48
	s_addc_u32 s43, s56, 0
	s_add_i32 s45, s45, s53
	s_lshl_b32 s45, s45, 6
	s_add_i32 s45, s45, s46
	s_lshl_b32 s44, s44, 5
	s_or_b32 s44, s45, s44
	s_or_b32 s44, s44, s54
	global_load_dwordx4 v[64:67], v[26:27], off
	global_load_dwordx4 v[68:71], v[24:25], off
	v_or_b32_e32 v26, s44, v112
	v_mov_b64_e32 v[24:25], s[42:43]
	v_mad_i64_i32 v[24:25], s[42:43], v26, s22, v[24:25]
	v_lshlrev_b32_e32 v104, 4, v76
	v_lshl_add_u64 v[36:37], v[24:25], 0, v[104:105]
	global_load_dwordx4 v[24:27], v[36:37], off
	global_load_dwordx4 v[28:31], v[36:37], off offset:64
	global_load_dwordx4 v[32:35], v[36:37], off offset:128
	s_nop 0
	global_load_dwordx4 v[36:39], v[36:37], off offset:192
	s_branch .LBB0_843

; template <int L>
; __device__ __forceinline__ void layer_body(const Args& args, LAS unsigned char* lds, const int wave, const int G, const int gw, const int NGW, const int lo, const int hi,
;                                            unsigned char* const ws_kernel, const XcdBarrier& bar, int& pid) {
;     ...
;                     if (tl_ < 15 * 31) rl[tl_] = rpb[h * 15 * 31 + tl_];
;                     __syncthreads();
.LBB0_3411:
	s_or_b64 exec, exec, s[0:1]
	s_add_i32 s0, s50, s53
	s_and_b32 s66, s0, 28
	v_add_u32_e32 v8, 64, v76
	v_add_u32_e32 v16, 0x80, v76
	v_add_u32_e32 v32, 0xc0, v76
	v_add_u32_e32 v48, 0x100, v76
	v_add_u32_e32 v56, 0x140, v76
	v_add_u32_e32 v66, 0x180, v76
	s_max_u32 s14, s66, 4
	v_med3_u32 v0, s66, 1, 25
	v_mul_hi_i32 v9, v8, s60
	v_mul_hi_i32 v17, v16, s60
	v_mul_hi_i32 v33, v32, s60
	v_mul_hi_i32 v49, v48, s60
	v_mul_hi_i32 v57, v56, s60
	v_mul_hi_i32 v67, v66, s60
	v_add_u32_e32 v2, 32, v76
	v_add_u32_e32 v10, 0x60, v76
	v_add_u32_e32 v18, 0xa0, v76
	v_add_u32_e32 v34, 0xe0, v76
	v_add_u32_e32 v50, 0x120, v76
	v_add_u32_e32 v58, 0x160, v76
	v_add_u32_e32 v68, 0x1a0, v76
	s_and_b32 s15, s40, 1
	s_lshl_b32 s0, s73, 8
	v_subrev_u32_e32 v0, s14, v0
	v_lshrrev_b32_e32 v11, 31, v9
	v_ashrrev_i32_e32 v9, 4, v9
	v_lshrrev_b32_e32 v19, 31, v17
	v_ashrrev_i32_e32 v17, 4, v17
	v_lshrrev_b32_e32 v35, 31, v33
	v_ashrrev_i32_e32 v33, 4, v33
	v_lshrrev_b32_e32 v51, 31, v49
	v_ashrrev_i32_e32 v49, 4, v49
	v_lshrrev_b32_e32 v59, 31, v57
	v_ashrrev_i32_e32 v57, 4, v57
	v_lshrrev_b32_e32 v71, 31, v67
	v_ashrrev_i32_e32 v67, 4, v67
	s_add_u32 s0, s46, s0
	v_add_u32_e32 v70, 10, v0
	v_mul_hi_i32 v0, v76, s60
	v_mul_hi_i32 v3, v2, s60
	v_add_u32_e32 v81, v9, v11
	v_mul_hi_i32 v11, v10, s60
	v_add_u32_e32 v85, v17, v19
	v_mul_hi_i32 v19, v18, s60
	v_add_u32_e32 v89, v33, v35
	v_mul_hi_i32 v35, v34, s60
	v_add_u32_e32 v93, v49, v51
	v_mul_hi_i32 v51, v50, s60
	v_add_u32_e32 v97, v57, v59
	v_mul_hi_i32 v59, v58, s60
	v_add_u32_e32 v102, v67, v71
	v_mul_hi_i32 v71, v68, s60
	s_addc_u32 s1, s47, 0
	v_lshrrev_b32_e32 v1, 31, v0
	v_ashrrev_i32_e32 v0, 4, v0
	v_lshrrev_b32_e32 v4, 31, v3
	v_ashrrev_i32_e32 v3, 4, v3
	v_lshrrev_b32_e32 v12, 31, v11
	v_ashrrev_i32_e32 v11, 4, v11
	v_lshrrev_b32_e32 v20, 31, v19
	v_ashrrev_i32_e32 v19, 4, v19
	v_lshrrev_b32_e32 v44, 31, v35
	v_ashrrev_i32_e32 v35, 4, v35
	v_lshrrev_b32_e32 v52, 31, v51
	v_ashrrev_i32_e32 v51, 4, v51
	v_lshrrev_b32_e32 v60, 31, v59
	v_ashrrev_i32_e32 v59, 4, v59
	v_lshrrev_b32_e32 v72, 31, v71
	v_ashrrev_i32_e32 v71, 4, v71
	v_lshl_add_u64 v[64:65], s[0:1], 0, v[104:105]
	s_add_i32 s0, s54, s57
	v_add_u32_e32 v77, v0, v1
	v_add_u32_e32 v79, v3, v4
	v_add_u32_e32 v83, v11, v12
	v_add_u32_e32 v87, v19, v20
	v_add_u32_e32 v91, v35, v44
	v_add_u32_e32 v95, v51, v52
	v_add_u32_e32 v100, v59, v60
	v_add_u32_e32 v113, v71, v72
	v_sub_u32_e64 v69, s66, 4 clamp
	s_and_b32 s8, s0, 0xfffff800
	s_mul_i32 s0, s15, 24
	v_min_i32_e32 v0, v77, v70
	v_min_i32_e32 v3, v79, v70
	v_min_i32_e32 v9, v81, v70
	v_min_i32_e32 v11, v83, v70
	v_min_i32_e32 v17, v85, v70
	v_min_i32_e32 v19, v87, v70
	v_min_i32_e32 v33, v89, v70
	v_min_i32_e32 v35, v91, v70
	v_min_i32_e32 v49, v93, v70
	v_min_i32_e32 v51, v95, v70
	v_min_i32_e32 v57, v97, v70
	v_min_i32_e32 v59, v100, v70
	v_min_i32_e32 v67, v102, v70
	v_min_i32_e32 v70, v113, v70
	s_or_b32 s16, s8, s0
	v_add_lshl_u32 v0, v0, v69, 6
	v_mad_i32_i24 v78, v77, s61, v76
	v_add_lshl_u32 v3, v3, v69, 6
	v_mad_i32_i24 v80, v79, s61, v2
	v_add_lshl_u32 v9, v9, v69, 6
	v_mad_i32_i24 v82, v81, s61, v8
	v_add_lshl_u32 v11, v11, v69, 6
	v_mad_i32_i24 v84, v83, s61, v10
	v_add_lshl_u32 v17, v17, v69, 6
	v_mad_i32_i24 v86, v85, s61, v16
	v_add_lshl_u32 v19, v19, v69, 6
	v_mad_i32_i24 v88, v87, s61, v18
	v_add_lshl_u32 v33, v33, v69, 6
	v_mad_i32_i24 v90, v89, s61, v32
	v_add_lshl_u32 v35, v35, v69, 6
	v_mad_i32_i24 v92, v91, s61, v34
	v_add_lshl_u32 v49, v49, v69, 6
	v_mad_i32_i24 v94, v93, s61, v48
	v_add_lshl_u32 v51, v51, v69, 6
	v_mad_i32_i24 v96, v95, s61, v50
	v_add_lshl_u32 v57, v57, v69, 6
	v_mad_i32_i24 v98, v97, s61, v56
	v_add_lshl_u32 v59, v59, v69, 6
	v_mad_i32_i24 v101, v100, s61, v58
	v_add_lshl_u32 v67, v67, v69, 6
	v_mad_i32_i24 v103, v102, s61, v66
	v_add_lshl_u32 v69, v70, v69, 6
	v_mad_i32_i24 v114, v113, s61, v68
	v_add3_u32 v0, v78, s16, v0
	v_add3_u32 v2, v80, s16, v3
	v_add3_u32 v8, v82, s16, v9
	v_add3_u32 v10, v84, s16, v11
	v_add3_u32 v16, v86, s16, v17
	v_add3_u32 v18, v88, s16, v19
	v_add3_u32 v32, v90, s16, v33
	v_add3_u32 v34, v92, s16, v35
	v_add3_u32 v48, v94, s16, v49
	v_add3_u32 v50, v96, s16, v51
	v_add3_u32 v56, v98, s16, v57
	v_add3_u32 v58, v101, s16, v59
	v_add3_u32 v66, v103, s16, v67
	v_add3_u32 v68, v114, s16, v69
	v_mad_i64_i32 v[0:1], s[0:1], v0, s62, v[64:65]
	v_mad_i64_i32 v[2:3], s[0:1], v2, s62, v[64:65]
	v_mad_i64_i32 v[8:9], s[0:1], v8, s62, v[64:65]
	v_mad_i64_i32 v[10:11], s[0:1], v10, s62, v[64:65]
	v_mad_i64_i32 v[16:17], s[0:1], v16, s62, v[64:65]
	v_mad_i64_i32 v[18:19], s[0:1], v18, s62, v[64:65]
	v_mad_i64_i32 v[32:33], s[0:1], v32, s62, v[64:65]
	v_mad_i64_i32 v[44:45], s[0:1], v34, s62, v[64:65]
	v_mad_i64_i32 v[48:49], s[0:1], v48, s62, v[64:65]
	v_mad_i64_i32 v[52:53], s[0:1], v50, s62, v[64:65]
	v_mad_i64_i32 v[56:57], s[0:1], v56, s62, v[64:65]
	v_mad_i64_i32 v[60:61], s[0:1], v58, s62, v[64:65]
	v_mad_i64_i32 v[66:67], s[0:1], v66, s62, v[64:65]
	v_mad_i64_i32 v[68:69], s[0:1], v68, s62, v[64:65]
	s_waitcnt lgkmcnt(0)
	s_barrier
; #define LAS __attribute__((address_space(3)))
; template <int L>
; __device__ __forceinline__ void layer_body(const Args& args, LAS unsigned char* lds, const int wave, const int G, const int gw, const int NGW, const int lo, const int hi,
;                                            unsigned char* const ws_kernel, const XcdBarrier& bar, int& pid) {
;     ...
;                     NA_LOADROWS(unit, rst, 2 * D);
;                     const int rr = wave >> 1, cb = 2 * hc + (wave & 1), r = rbase + rr, r0w = min(max(r - 4, 0), 24), cs = min(max(16 * cb - 8, 0), 32), coloff = cs - 24 * hc;
;                     const int c = 16 * cb + qi, wsq = min(max(c - 8, 0), 48);
;                     f32x4 sc[16];
; #pragma unroll
;                     for (int t = 0; t < 16; ++t) {
;                         const int irow = (r0w - krlo + (t >> 1)) * 40 + coloff + 16 * (t & 1);
;                         const unsigned ka = IMG + (unsigned)((irow + qi) * KPITCH + 16 * kg);
;                         f32x4 a = (f32x4){0.f, 0.f, 0.f, 0.f};
; #pragma unroll
;                         for (int ks = 0; ks < 4; ++ks) a = __builtin_amdgcn_mfma_f32_16x16x32_bf16(*(const LAS bf16x8*)(size_t)(ka + 64 * ks), qfn[ks], a, 0, 0, 0);
;                         const int dr = r0w + (t >> 1) - r + 7;
; #pragma unroll
;                         for (int j = 0; j < 4; ++j) { const int kc = cs + 16 * (t & 1) + 4 * kg + j; const bool valid = (kc >= wsq) && (kc < wsq + 16); const int dc = min(max(kc - c + 15, 0), 30);
;                             sc[t][j] = valid ? a[j] * scale_log2 + rl[dr * 31 + dc] * LOG2E : -1e30f; }
	global_load_dwordx4 v[4:7], v[0:1], off
	s_nop 0
	global_load_dwordx4 v[0:3], v[2:3], off
	s_nop 0
	global_load_dwordx4 v[12:15], v[8:9], off
	s_nop 0
	global_load_dwordx4 v[8:11], v[10:11], off
	s_nop 0
	global_load_dwordx4 v[20:23], v[16:17], off
	s_nop 0
	global_load_dwordx4 v[16:19], v[18:19], off
	s_nop 0
	global_load_dwordx4 v[32:35], v[32:33], off
	s_nop 0
	global_load_dwordx4 v[44:47], v[44:45], off
	s_nop 0
	global_load_dwordx4 v[48:51], v[48:49], off
	s_nop 0
	global_load_dwordx4 v[52:55], v[52:53], off
	s_nop 0
	global_load_dwordx4 v[56:59], v[56:57], off
	s_nop 0
	global_load_dwordx4 v[60:63], v[60:61], off
	s_nop 0
	global_load_dwordx4 v[64:67], v[66:67], off
	s_nop 0
	global_load_dwordx4 v[68:71], v[68:69], off
	s_add_i32 s66, s66, s42
	s_lshl_b32 s1, s15, 5
	s_max_i32 s0, s66, 4
	s_or_b32 s1, s1, s43
	s_add_i32 s0, s0, -4
	s_max_i32 s16, s1, 8
	s_min_u32 s0, s0, 24
	s_add_i32 s16, s16, -8
	s_min_u32 s16, s16, 32
	s_mulk_i32 s15, 0xffe8
	s_sub_i32 s76, s0, s14
	s_add_i32 s67, s16, s15
	s_mul_i32 s76, s76, 40
	v_bfe_u32 v99, v111, 4, 2
	v_add_u32_e32 v123, s67, v112
	s_add_i32 s68, s76, 0xa0
	v_lshl_add_u32 v118, v99, 4, 0
	v_add_u32_e32 v72, s68, v123
	v_mad_i32_i24 v104, v72, s58, v118
	ds_read_b128 v[72:75], v104
	ds_read_b128 v[124:127], v104 offset:64
	ds_read_b128 v[128:131], v104 offset:128
	s_waitcnt lgkmcnt(2)
	v_mfma_f32_16x16x32_bf16 v[72:75], v[72:75], v[24:27], 0
	ds_read_b128 v[136:139], v104 offset:192
	v_or_b32_e32 v110, s1, v112
	v_max_i32_e32 v109, 8, v110
	s_waitcnt lgkmcnt(2)
	v_mfma_f32_16x16x32_bf16 v[72:75], v[124:127], v[28:31], v[72:75]
	v_add_u32_e32 v104, -8, v109
	v_min_u32_e32 v126, 48, v104
	s_sub_i32 s0, s0, s66
	s_waitcnt lgkmcnt(1)
	v_mfma_f32_16x16x32_bf16 v[72:75], v[128:131], v[36:39], v[72:75]
	v_lshlrev_b32_e32 v109, 2, v99
	v_add_u32_e32 v134, s16, v109
	v_add_u32_e32 v128, 16, v126
	s_waitcnt lgkmcnt(0)
	v_mfma_f32_16x16x32_bf16 v[72:75], v[136:139], v[40:43], v[72:75]
	s_mulk_i32 s0, 0x7c
	s_add_i32 s77, s0, 0
	v_cmp_ge_u32_e32 vcc, v134, v126
	v_cmp_lt_u32_e64 s[0:1], v134, v128
	v_sub_u32_e32 v115, v134, v110
	s_add_i32 s77, s77, 0x1dc00
	s_and_b64 s[14:15], vcc, s[0:1]
	v_max_i32_e32 v124, -15, v115
	v_mov_b32_e32 v202, 0xf149f2ca
	s_nop 1
	v_add_u32_e32 v201, 15, v124
	v_min_u32_e32 v201, 30, v201
	v_lshl_add_u32 v213, v201, 2, s77
	ds_read_b32 v201, v213 offset:868
	s_nop 0
	s_waitcnt lgkmcnt(0)
	v_fma_f32 v200, v72, s12, v201
	v_cndmask_b32_e64 v115, v202, v200, s[14:15]
	v_or_b32_e32 v72, 1, v134
	v_cmp_ge_u32_e32 vcc, v72, v126
	v_cmp_lt_u32_e64 s[0:1], v72, v128
	v_sub_u32_e32 v72, v72, v110
	s_and_b64 s[16:17], vcc, s[0:1]
	v_max_i32_e32 v125, -15, v72
	s_nop 1
	v_add_u32_e32 v215, 15, v125
	v_min_u32_e32 v215, 30, v215
	v_lshl_add_u32 v220, v215, 2, s77
	ds_read_b32 v215, v220 offset:868
	s_nop 0
	s_waitcnt lgkmcnt(0)
	v_fma_f32 v214, v73, s12, v215
	v_cndmask_b32_e64 v104, v202, v214, s[16:17]
	v_or_b32_e32 v72, 2, v134
	v_cmp_ge_u32_e32 vcc, v72, v126
	v_cmp_lt_u32_e64 s[0:1], v72, v128
	v_sub_u32_e32 v72, v72, v110
	s_and_b64 s[20:21], vcc, s[0:1]
	v_max_i32_e32 v127, -15, v72
	s_nop 1
	v_add_u32_e32 v217, 15, v127
	v_min_u32_e32 v217, 30, v217
	v_lshl_add_u32 v221, v217, 2, s77
	ds_read_b32 v217, v221 offset:868
	s_nop 0
	s_waitcnt lgkmcnt(0)
	v_fma_f32 v216, v74, s12, v217
	v_cndmask_b32_e64 v117, v202, v216, s[20:21]
	v_or_b32_e32 v72, 3, v134
	v_cmp_ge_u32_e32 vcc, v72, v126
	v_cmp_lt_u32_e64 s[0:1], v72, v128
	v_sub_u32_e32 v72, v72, v110
	s_and_b64 s[22:23], vcc, s[0:1]
	v_max_i32_e32 v129, -15, v72
	s_nop 1
	v_add_u32_e32 v219, 15, v129
	v_min_u32_e32 v219, 30, v219
	v_lshl_add_u32 v222, v219, 2, s77
	ds_read_b32 v219, v222 offset:868
	s_nop 0
	s_waitcnt lgkmcnt(0)
	v_fma_f32 v218, v75, s12, v219
	v_cndmask_b32_e64 v116, v202, v218, s[22:23]
	v_add_u32_e32 v130, 16, v123
	v_add_u32_e32 v72, s68, v130
	v_mad_i32_i24 v119, v72, s58, v118
	ds_read_b128 v[72:75], v119
	ds_read_b128 v[136:139], v119 offset:64
	ds_read_b128 v[140:143], v119 offset:128
	v_add_u32_e32 v120, 16, v134
	v_cmp_lt_u32_e32 vcc, v134, v126
	s_waitcnt lgkmcnt(2)
	v_mfma_f32_16x16x32_bf16 v[72:75], v[72:75], v[24:27], 0
	v_cmp_ge_u32_e64 s[0:1], v120, v126
	v_sub_u32_e32 v120, v120, v110
	s_and_b64 s[24:25], s[0:1], vcc
	s_waitcnt lgkmcnt(1)
	v_mfma_f32_16x16x32_bf16 v[72:75], v[136:139], v[28:31], v[72:75]
	ds_read_b128 v[136:139], v119 offset:192
	v_max_i32_e32 v131, -15, v120
	s_waitcnt lgkmcnt(1)
	v_mfma_f32_16x16x32_bf16 v[72:75], v[140:143], v[36:39], v[72:75]
	s_waitcnt lgkmcnt(0)
	v_mfma_f32_16x16x32_bf16 v[72:75], v[136:139], v[40:43], v[72:75]
	s_nop 1
	v_add_u32_e32 v201, 15, v131
	v_min_u32_e32 v201, 30, v201
	v_lshl_add_u32 v223, v201, 2, s77
	ds_read_b32 v201, v223 offset:868
	s_nop 1
	s_nop 0
	s_waitcnt lgkmcnt(0)
	v_fma_f32 v200, v72, s12, v201
	v_cndmask_b32_e64 v120, v202, v200, s[24:25]
	s_nop 4
	v_add_u32_e32 v72, 17, v134
	v_cmp_ge_u32_e32 vcc, v72, v126
	v_cmp_lt_u32_e64 s[0:1], v72, v128
	v_sub_u32_e32 v72, v72, v110
	s_and_b64 s[26:27], vcc, s[0:1]
	v_max_i32_e32 v132, -15, v72
	s_nop 1
	v_add_u32_e32 v215, 15, v132
	v_min_u32_e32 v215, 30, v215
	v_lshl_add_u32 v224, v215, 2, s77
	ds_read_b32 v215, v224 offset:868
	s_nop 0
	s_waitcnt lgkmcnt(0)
	v_fma_f32 v214, v73, s12, v215
	v_cndmask_b32_e64 v119, v202, v214, s[26:27]
	v_add_u32_e32 v72, 18, v134
	v_cmp_ge_u32_e32 vcc, v72, v126
	v_cmp_lt_u32_e64 s[0:1], v72, v128
	v_sub_u32_e32 v72, v72, v110
	s_and_b64 s[36:37], vcc, s[0:1]
	v_max_i32_e32 v133, -15, v72
	s_nop 1
	v_add_u32_e32 v217, 15, v133
	v_min_u32_e32 v217, 30, v217
	v_lshl_add_u32 v225, v217, 2, s77
	ds_read_b32 v217, v225 offset:868
	s_nop 0
	s_waitcnt lgkmcnt(0)
; #define LAS __attribute__((address_space(3)))
; template <int L>
; __device__ __forceinline__ void layer_body(const Args& args, LAS unsigned char* lds, const int wave, const int G, const int gw, const int NGW, const int lo, const int hi,
;                                            unsigned char* const ws_kernel, const XcdBarrier& bar, int& pid) {
;     ...
; #pragma unroll
;                     for (int t = 0; t < 16; ++t) {
;                         const int irow = (r0w - krlo + (t >> 1)) * 40 + coloff + 16 * (t & 1);
;                         const unsigned ka = IMG + (unsigned)((irow + qi) * KPITCH + 16 * kg);
;                         f32x4 a = (f32x4){0.f, 0.f, 0.f, 0.f};
; #pragma unroll
;                         for (int ks = 0; ks < 4; ++ks) a = __builtin_amdgcn_mfma_f32_16x16x32_bf16(*(const LAS bf16x8*)(size_t)(ka + 64 * ks), qfn[ks], a, 0, 0, 0);
;                         const int dr = r0w + (t >> 1) - r + 7;
; #pragma unroll
;                         for (int j = 0; j < 4; ++j) { const int kc = cs + 16 * (t & 1) + 4 * kg + j; const bool valid = (kc >= wsq) && (kc < wsq + 16); const int dc = min(max(kc - c + 15, 0), 30);
;                             sc[t][j] = valid ? a[j] * scale_log2 + rl[dr * 31 + dc] * LOG2E : -1e30f; }
;                         __builtin_amdgcn_sched_barrier(0);
;                     }
	v_fma_f32 v216, v74, s12, v217
	v_cndmask_b32_e64 v122, v202, v216, s[36:37]
	v_add_u32_e32 v72, 19, v134
	v_cmp_ge_u32_e32 vcc, v72, v126
	v_cmp_lt_u32_e64 s[0:1], v72, v128
	v_sub_u32_e32 v72, v72, v110
	s_and_b64 s[0:1], vcc, s[0:1]
	v_max_i32_e32 v134, -15, v72
	s_nop 1
	v_add_u32_e32 v219, 15, v134
	v_min_u32_e32 v219, 30, v219
	v_lshl_add_u32 v226, v219, 2, s77
	ds_read_b32 v219, v226 offset:868
	s_nop 0
	s_waitcnt lgkmcnt(0)
	v_fma_f32 v218, v75, s12, v219
	v_cndmask_b32_e64 v121, v202, v218, s[0:1]
	s_add_i32 s69, s76, 0xc8
	v_add_u32_e32 v72, s69, v123
	v_mad_i32_i24 v126, v72, s58, v118
	ds_read_b128 v[72:75], v126
	ds_read_b128 v[136:139], v126 offset:64
	ds_read_b128 v[140:143], v126 offset:128
	ds_read_b128 v[228:231], v126 offset:192
	ds_read_b32 v201, v213 offset:992
	ds_read_b32 v215, v220 offset:992
	ds_read_b32 v217, v221 offset:992
	ds_read_b32 v219, v222 offset:992
	s_waitcnt lgkmcnt(7)
	v_mfma_f32_16x16x32_bf16 v[72:75], v[72:75], v[24:27], 0
	s_waitcnt lgkmcnt(6)
	v_mfma_f32_16x16x32_bf16 v[72:75], v[136:139], v[28:31], v[72:75]
	s_waitcnt lgkmcnt(5)
	v_mfma_f32_16x16x32_bf16 v[72:75], v[140:143], v[36:39], v[72:75]
	s_waitcnt lgkmcnt(4)
	v_mfma_f32_16x16x32_bf16 v[72:75], v[228:231], v[40:43], v[72:75]
	s_nop 7
	s_waitcnt lgkmcnt(0)
	v_fma_f32 v200, v72, s12, v201
	v_fma_f32 v214, v73, s12, v215
	v_fma_f32 v216, v74, s12, v217
	v_fma_f32 v218, v75, s12, v219
	v_cndmask_b32_e64 v128, v202, v200, s[14:15]
	v_cndmask_b32_e64 v126, v202, v214, s[16:17]
	v_cndmask_b32_e64 v136, v202, v216, s[20:21]
	v_cndmask_b32_e64 v135, v202, v218, s[22:23]
	v_add_u32_e32 v72, s69, v130
	v_mad_i32_i24 v137, v72, s58, v118
	ds_read_b128 v[72:75], v137
	ds_read_b128 v[138:141], v137 offset:64
	ds_read_b128 v[142:145], v137 offset:128
	ds_read_b128 v[228:231], v137 offset:192
	ds_read_b32 v201, v223 offset:992
	ds_read_b32 v215, v224 offset:992
	ds_read_b32 v217, v225 offset:992
	ds_read_b32 v219, v226 offset:992
	s_waitcnt lgkmcnt(7)
	v_mfma_f32_16x16x32_bf16 v[72:75], v[72:75], v[24:27], 0
	s_waitcnt lgkmcnt(6)
	v_mfma_f32_16x16x32_bf16 v[72:75], v[138:141], v[28:31], v[72:75]
	s_waitcnt lgkmcnt(5)
	v_mfma_f32_16x16x32_bf16 v[72:75], v[142:145], v[36:39], v[72:75]
	s_waitcnt lgkmcnt(4)
	v_mfma_f32_16x16x32_bf16 v[72:75], v[228:231], v[40:43], v[72:75]
	s_nop 7
	s_waitcnt lgkmcnt(0)
	v_fma_f32 v200, v72, s12, v201
	v_fma_f32 v214, v73, s12, v215
	v_fma_f32 v216, v74, s12, v217
	v_fma_f32 v218, v75, s12, v219
	v_cndmask_b32_e64 v138, v202, v200, s[24:25]
	v_cndmask_b32_e64 v137, v202, v214, s[26:27]
	v_cndmask_b32_e64 v140, v202, v216, s[36:37]
	v_cndmask_b32_e64 v139, v202, v218, s[0:1]
	s_add_i32 s70, s76, 0xf0
	v_add_u32_e32 v72, s70, v123
	v_mad_i32_i24 v141, v72, s58, v118
	ds_read_b128 v[72:75], v141
	ds_read_b128 v[142:145], v141 offset:64
	ds_read_b128 v[146:149], v141 offset:128
	ds_read_b128 v[228:231], v141 offset:192
	ds_read_b32 v201, v213 offset:1116
	ds_read_b32 v215, v220 offset:1116
	ds_read_b32 v217, v221 offset:1116
	ds_read_b32 v219, v222 offset:1116
	s_waitcnt lgkmcnt(7)
	v_mfma_f32_16x16x32_bf16 v[72:75], v[72:75], v[24:27], 0
	s_waitcnt lgkmcnt(6)
	v_mfma_f32_16x16x32_bf16 v[72:75], v[142:145], v[28:31], v[72:75]
	s_waitcnt lgkmcnt(5)
	v_mfma_f32_16x16x32_bf16 v[72:75], v[146:149], v[36:39], v[72:75]
	s_waitcnt lgkmcnt(4)
	v_mfma_f32_16x16x32_bf16 v[72:75], v[228:231], v[40:43], v[72:75]
	s_nop 7
	s_waitcnt lgkmcnt(0)
	v_fma_f32 v200, v72, s12, v201
	v_fma_f32 v214, v73, s12, v215
	v_fma_f32 v216, v74, s12, v217
	v_fma_f32 v218, v75, s12, v219
	v_cndmask_b32_e64 v142, v202, v200, s[14:15]
	v_cndmask_b32_e64 v141, v202, v214, s[16:17]
	v_cndmask_b32_e64 v144, v202, v216, s[20:21]
	v_cndmask_b32_e64 v143, v202, v218, s[22:23]
	v_add_u32_e32 v72, s70, v130
	v_mad_i32_i24 v145, v72, s58, v118
	ds_read_b128 v[72:75], v145
	ds_read_b128 v[146:149], v145 offset:64
	ds_read_b128 v[150:153], v145 offset:128
	ds_read_b128 v[228:231], v145 offset:192
	ds_read_b32 v201, v223 offset:1116
	ds_read_b32 v215, v224 offset:1116
	ds_read_b32 v217, v225 offset:1116
	ds_read_b32 v219, v226 offset:1116
	s_waitcnt lgkmcnt(7)
	v_mfma_f32_16x16x32_bf16 v[72:75], v[72:75], v[24:27], 0
	s_waitcnt lgkmcnt(6)
	v_mfma_f32_16x16x32_bf16 v[72:75], v[146:149], v[28:31], v[72:75]
	s_waitcnt lgkmcnt(5)
	v_mfma_f32_16x16x32_bf16 v[72:75], v[150:153], v[36:39], v[72:75]
	s_waitcnt lgkmcnt(4)
	v_mfma_f32_16x16x32_bf16 v[72:75], v[228:231], v[40:43], v[72:75]
	s_nop 7
	s_waitcnt lgkmcnt(0)
	v_fma_f32 v200, v72, s12, v201
	v_fma_f32 v214, v73, s12, v215
	v_fma_f32 v216, v74, s12, v217
	v_fma_f32 v218, v75, s12, v219
	v_cndmask_b32_e64 v146, v202, v200, s[24:25]
	v_cndmask_b32_e64 v145, v202, v214, s[26:27]
	v_cndmask_b32_e64 v148, v202, v216, s[36:37]
	v_cndmask_b32_e64 v147, v202, v218, s[0:1]
	s_add_i32 s71, s76, 0x118
	v_add_u32_e32 v72, s71, v123
	v_mad_i32_i24 v149, v72, s58, v118
	ds_read_b128 v[72:75], v149
	ds_read_b128 v[150:153], v149 offset:64
	ds_read_b128 v[154:157], v149 offset:128
	ds_read_b128 v[228:231], v149 offset:192
	ds_read_b32 v201, v213 offset:1240
	ds_read_b32 v215, v220 offset:1240
	ds_read_b32 v217, v221 offset:1240
	ds_read_b32 v219, v222 offset:1240
	s_waitcnt lgkmcnt(7)
	v_mfma_f32_16x16x32_bf16 v[72:75], v[72:75], v[24:27], 0
	s_waitcnt lgkmcnt(6)
	v_mfma_f32_16x16x32_bf16 v[72:75], v[150:153], v[28:31], v[72:75]
	s_waitcnt lgkmcnt(5)
	v_mfma_f32_16x16x32_bf16 v[72:75], v[154:157], v[36:39], v[72:75]
	s_waitcnt lgkmcnt(4)
	v_mfma_f32_16x16x32_bf16 v[72:75], v[228:231], v[40:43], v[72:75]
	s_nop 7
	s_waitcnt lgkmcnt(0)
; #define LAS __attribute__((address_space(3)))
; template <int L>
; __device__ __forceinline__ void layer_body(const Args& args, LAS unsigned char* lds, const int wave, const int G, const int gw, const int NGW, const int lo, const int hi,
;                                            unsigned char* const ws_kernel, const XcdBarrier& bar, int& pid) {
;     ...
; #pragma unroll
;                     for (int t = 0; t < 16; ++t) {
;                         const int irow = (r0w - krlo + (t >> 1)) * 40 + coloff + 16 * (t & 1);
;                         const unsigned ka = IMG + (unsigned)((irow + qi) * KPITCH + 16 * kg);
;                         f32x4 a = (f32x4){0.f, 0.f, 0.f, 0.f};
; #pragma unroll
;                         for (int ks = 0; ks < 4; ++ks) a = __builtin_amdgcn_mfma_f32_16x16x32_bf16(*(const LAS bf16x8*)(size_t)(ka + 64 * ks), qfn[ks], a, 0, 0, 0);
;                         const int dr = r0w + (t >> 1) - r + 7;
; #pragma unroll
;                         for (int j = 0; j < 4; ++j) { const int kc = cs + 16 * (t & 1) + 4 * kg + j; const bool valid = (kc >= wsq) && (kc < wsq + 16); const int dc = min(max(kc - c + 15, 0), 30);
;                             sc[t][j] = valid ? a[j] * scale_log2 + rl[dr * 31 + dc] * LOG2E : -1e30f; }
;                         __builtin_amdgcn_sched_barrier(0);
;                     }
	v_fma_f32 v200, v72, s12, v201
	v_fma_f32 v214, v73, s12, v215
	v_fma_f32 v216, v74, s12, v217
	v_fma_f32 v218, v75, s12, v219
	v_cndmask_b32_e64 v150, v202, v200, s[14:15]
	v_cndmask_b32_e64 v149, v202, v214, s[16:17]
	v_cndmask_b32_e64 v152, v202, v216, s[20:21]
	v_cndmask_b32_e64 v151, v202, v218, s[22:23]
	v_add_u32_e32 v72, s71, v130
	v_mad_i32_i24 v153, v72, s58, v118
	ds_read_b128 v[72:75], v153
	ds_read_b128 v[154:157], v153 offset:64
	ds_read_b128 v[158:161], v153 offset:128
	ds_read_b128 v[228:231], v153 offset:192
	ds_read_b32 v201, v223 offset:1240
	ds_read_b32 v215, v224 offset:1240
	ds_read_b32 v217, v225 offset:1240
	ds_read_b32 v219, v226 offset:1240
	s_waitcnt lgkmcnt(7)
	v_mfma_f32_16x16x32_bf16 v[72:75], v[72:75], v[24:27], 0
	s_waitcnt lgkmcnt(6)
	v_mfma_f32_16x16x32_bf16 v[72:75], v[154:157], v[28:31], v[72:75]
	s_waitcnt lgkmcnt(5)
	v_mfma_f32_16x16x32_bf16 v[72:75], v[158:161], v[36:39], v[72:75]
	s_waitcnt lgkmcnt(4)
	v_mfma_f32_16x16x32_bf16 v[72:75], v[228:231], v[40:43], v[72:75]
	s_nop 7
	s_waitcnt lgkmcnt(0)
	v_fma_f32 v200, v72, s12, v201
	v_fma_f32 v214, v73, s12, v215
	v_fma_f32 v216, v74, s12, v217
	v_fma_f32 v218, v75, s12, v219
	v_cndmask_b32_e64 v154, v202, v200, s[24:25]
	v_cndmask_b32_e64 v153, v202, v214, s[26:27]
	v_cndmask_b32_e64 v156, v202, v216, s[36:37]
	v_cndmask_b32_e64 v155, v202, v218, s[0:1]
	s_add_i32 s72, s76, 0x140
	v_add_u32_e32 v72, s72, v123
	v_mad_i32_i24 v157, v72, s58, v118
	ds_read_b128 v[72:75], v157
	ds_read_b128 v[158:161], v157 offset:64
	ds_read_b128 v[162:165], v157 offset:128
	ds_read_b128 v[228:231], v157 offset:192
	ds_read_b32 v201, v213 offset:1364
	ds_read_b32 v215, v220 offset:1364
	ds_read_b32 v217, v221 offset:1364
	ds_read_b32 v219, v222 offset:1364
	s_waitcnt lgkmcnt(7)
	v_mfma_f32_16x16x32_bf16 v[72:75], v[72:75], v[24:27], 0
	s_waitcnt lgkmcnt(6)
	v_mfma_f32_16x16x32_bf16 v[72:75], v[158:161], v[28:31], v[72:75]
	s_waitcnt lgkmcnt(5)
	v_mfma_f32_16x16x32_bf16 v[72:75], v[162:165], v[36:39], v[72:75]
	s_waitcnt lgkmcnt(4)
	v_mfma_f32_16x16x32_bf16 v[72:75], v[228:231], v[40:43], v[72:75]
	s_nop 7
	s_waitcnt lgkmcnt(0)
	v_fma_f32 v200, v72, s12, v201
	v_fma_f32 v214, v73, s12, v215
	v_fma_f32 v216, v74, s12, v217
	v_fma_f32 v218, v75, s12, v219
	v_cndmask_b32_e64 v158, v202, v200, s[14:15]
	v_cndmask_b32_e64 v157, v202, v214, s[16:17]
	v_cndmask_b32_e64 v160, v202, v216, s[20:21]
	v_cndmask_b32_e64 v159, v202, v218, s[22:23]
	v_add_u32_e32 v72, s72, v130
	v_mad_i32_i24 v161, v72, s58, v118
	ds_read_b128 v[72:75], v161
	ds_read_b128 v[162:165], v161 offset:64
	ds_read_b128 v[166:169], v161 offset:128
	ds_read_b128 v[228:231], v161 offset:192
	ds_read_b32 v201, v223 offset:1364
	ds_read_b32 v215, v224 offset:1364
	ds_read_b32 v217, v225 offset:1364
	ds_read_b32 v219, v226 offset:1364
	s_waitcnt lgkmcnt(7)
	v_mfma_f32_16x16x32_bf16 v[72:75], v[72:75], v[24:27], 0
	s_waitcnt lgkmcnt(6)
	v_mfma_f32_16x16x32_bf16 v[72:75], v[162:165], v[28:31], v[72:75]
	s_waitcnt lgkmcnt(5)
	v_mfma_f32_16x16x32_bf16 v[72:75], v[166:169], v[36:39], v[72:75]
	s_waitcnt lgkmcnt(4)
	v_mfma_f32_16x16x32_bf16 v[72:75], v[228:231], v[40:43], v[72:75]
	s_nop 7
	s_waitcnt lgkmcnt(0)
	v_fma_f32 v200, v72, s12, v201
	v_fma_f32 v214, v73, s12, v215
	v_fma_f32 v216, v74, s12, v217
	v_fma_f32 v218, v75, s12, v219
	v_cndmask_b32_e64 v162, v202, v200, s[24:25]
	v_cndmask_b32_e64 v161, v202, v214, s[26:27]
	v_cndmask_b32_e64 v164, v202, v216, s[36:37]
	v_cndmask_b32_e64 v163, v202, v218, s[0:1]
	s_add_i32 s74, s76, 0x168
	v_add_u32_e32 v72, s74, v123
	v_mad_i32_i24 v165, v72, s58, v118
	ds_read_b128 v[72:75], v165
	ds_read_b128 v[166:169], v165 offset:64
	ds_read_b128 v[170:173], v165 offset:128
	ds_read_b128 v[228:231], v165 offset:192
	ds_read_b32 v201, v213 offset:1488
	ds_read_b32 v215, v220 offset:1488
	ds_read_b32 v217, v221 offset:1488
	ds_read_b32 v219, v222 offset:1488
	s_waitcnt lgkmcnt(7)
	v_mfma_f32_16x16x32_bf16 v[72:75], v[72:75], v[24:27], 0
	s_waitcnt lgkmcnt(6)
	v_mfma_f32_16x16x32_bf16 v[72:75], v[166:169], v[28:31], v[72:75]
	s_waitcnt lgkmcnt(5)
	v_mfma_f32_16x16x32_bf16 v[72:75], v[170:173], v[36:39], v[72:75]
	s_waitcnt lgkmcnt(4)
	v_mfma_f32_16x16x32_bf16 v[72:75], v[228:231], v[40:43], v[72:75]
	s_nop 7
	s_waitcnt lgkmcnt(0)
	v_fma_f32 v200, v72, s12, v201
	v_fma_f32 v214, v73, s12, v215
	v_fma_f32 v216, v74, s12, v217
	v_fma_f32 v218, v75, s12, v219
	v_cndmask_b32_e64 v166, v202, v200, s[14:15]
	v_cndmask_b32_e64 v165, v202, v214, s[16:17]
	v_cndmask_b32_e64 v168, v202, v216, s[20:21]
	v_cndmask_b32_e64 v167, v202, v218, s[22:23]
	v_add_u32_e32 v72, s74, v130
	v_mad_i32_i24 v169, v72, s58, v118
	ds_read_b128 v[72:75], v169
	ds_read_b128 v[170:173], v169 offset:64
	ds_read_b128 v[174:177], v169 offset:128
	ds_read_b128 v[228:231], v169 offset:192
	ds_read_b32 v201, v223 offset:1488
	ds_read_b32 v215, v224 offset:1488
	ds_read_b32 v217, v225 offset:1488
	ds_read_b32 v219, v226 offset:1488
	s_waitcnt lgkmcnt(7)
	v_mfma_f32_16x16x32_bf16 v[72:75], v[72:75], v[24:27], 0
	s_waitcnt lgkmcnt(6)
	v_mfma_f32_16x16x32_bf16 v[72:75], v[170:173], v[28:31], v[72:75]
	s_waitcnt lgkmcnt(5)
	v_mfma_f32_16x16x32_bf16 v[72:75], v[174:177], v[36:39], v[72:75]
	s_waitcnt lgkmcnt(4)
	v_mfma_f32_16x16x32_bf16 v[72:75], v[228:231], v[40:43], v[72:75]
	s_nop 7
	s_waitcnt lgkmcnt(0)
; #define LAS __attribute__((address_space(3)))
; template <int L>
; __device__ __forceinline__ void layer_body(const Args& args, LAS unsigned char* lds, const int wave, const int G, const int gw, const int NGW, const int lo, const int hi,
;                                            unsigned char* const ws_kernel, const XcdBarrier& bar, int& pid) {
;     ...
; #pragma unroll
;                     for (int t = 0; t < 16; ++t) {
;                         const int irow = (r0w - krlo + (t >> 1)) * 40 + coloff + 16 * (t & 1);
;                         const unsigned ka = IMG + (unsigned)((irow + qi) * KPITCH + 16 * kg);
;                         f32x4 a = (f32x4){0.f, 0.f, 0.f, 0.f};
; #pragma unroll
;                         for (int ks = 0; ks < 4; ++ks) a = __builtin_amdgcn_mfma_f32_16x16x32_bf16(*(const LAS bf16x8*)(size_t)(ka + 64 * ks), qfn[ks], a, 0, 0, 0);
;                         const int dr = r0w + (t >> 1) - r + 7;
; #pragma unroll
;                         for (int j = 0; j < 4; ++j) { const int kc = cs + 16 * (t & 1) + 4 * kg + j; const bool valid = (kc >= wsq) && (kc < wsq + 16); const int dc = min(max(kc - c + 15, 0), 30);
;                             sc[t][j] = valid ? a[j] * scale_log2 + rl[dr * 31 + dc] * LOG2E : -1e30f; }
;                         __builtin_amdgcn_sched_barrier(0);
;                     }
;                     float mx = -1e30f;
; #pragma unroll
;                     for (int t = 0; t < 16; ++t)
; #pragma unroll
;                         for (int j = 0; j < 4; ++j) mx = fmaxf(mx, sc[t][j]);
;                     mx = fmaxf(mx, __shfl_xor(mx, 16)); mx = fmaxf(mx, __shfl_xor(mx, 32));
	v_fma_f32 v200, v72, s12, v201
	v_fma_f32 v214, v73, s12, v215
	v_fma_f32 v216, v74, s12, v217
	v_fma_f32 v218, v75, s12, v219
	v_cndmask_b32_e64 v170, v202, v200, s[24:25]
	v_cndmask_b32_e64 v169, v202, v214, s[26:27]
	v_cndmask_b32_e64 v172, v202, v216, s[36:37]
	v_cndmask_b32_e64 v171, v202, v218, s[0:1]
	s_add_i32 s75, s76, 0x190
	v_add_u32_e32 v72, s75, v123
	v_mad_i32_i24 v173, v72, s58, v118
	ds_read_b128 v[72:75], v173
	ds_read_b128 v[174:177], v173 offset:64
	ds_read_b128 v[178:181], v173 offset:128
	ds_read_b128 v[228:231], v173 offset:192
	ds_read_b32 v201, v213 offset:1612
	ds_read_b32 v215, v220 offset:1612
	ds_read_b32 v217, v221 offset:1612
	ds_read_b32 v219, v222 offset:1612
	s_waitcnt lgkmcnt(7)
	v_mfma_f32_16x16x32_bf16 v[72:75], v[72:75], v[24:27], 0
	s_waitcnt lgkmcnt(6)
	v_mfma_f32_16x16x32_bf16 v[72:75], v[174:177], v[28:31], v[72:75]
	s_waitcnt lgkmcnt(5)
	v_mfma_f32_16x16x32_bf16 v[72:75], v[178:181], v[36:39], v[72:75]
	s_waitcnt lgkmcnt(4)
	v_mfma_f32_16x16x32_bf16 v[72:75], v[228:231], v[40:43], v[72:75]
	s_nop 7
	s_waitcnt lgkmcnt(0)
	v_fma_f32 v200, v72, s12, v201
	v_fma_f32 v214, v73, s12, v215
	v_fma_f32 v216, v74, s12, v217
	v_fma_f32 v218, v75, s12, v219
	v_cndmask_b32_e64 v174, v202, v200, s[14:15]
	v_cndmask_b32_e64 v173, v202, v214, s[16:17]
	v_cndmask_b32_e64 v176, v202, v216, s[20:21]
	v_cndmask_b32_e64 v175, v202, v218, s[22:23]
	v_add_u32_e32 v72, s75, v130
	v_mad_i32_i24 v177, v72, s58, v118
	ds_read_b128 v[72:75], v177
	ds_read_b128 v[178:181], v177 offset:64
	ds_read_b128 v[182:185], v177 offset:128
	ds_read_b128 v[228:231], v177 offset:192
	ds_read_b32 v201, v223 offset:1612
	ds_read_b32 v215, v224 offset:1612
	ds_read_b32 v217, v225 offset:1612
	ds_read_b32 v219, v226 offset:1612
	s_waitcnt lgkmcnt(7)
	v_mfma_f32_16x16x32_bf16 v[72:75], v[72:75], v[24:27], 0
	s_waitcnt lgkmcnt(6)
	v_mfma_f32_16x16x32_bf16 v[72:75], v[178:181], v[28:31], v[72:75]
	s_waitcnt lgkmcnt(5)
	v_mfma_f32_16x16x32_bf16 v[72:75], v[182:185], v[36:39], v[72:75]
	s_waitcnt lgkmcnt(4)
	v_mfma_f32_16x16x32_bf16 v[72:75], v[228:231], v[40:43], v[72:75]
	s_nop 7
	s_waitcnt lgkmcnt(0)
	v_fma_f32 v200, v72, s12, v201
	v_fma_f32 v214, v73, s12, v215
	v_fma_f32 v216, v74, s12, v217
	v_fma_f32 v218, v75, s12, v219
	v_cndmask_b32_e64 v183, v202, v200, s[24:25]
	v_cndmask_b32_e64 v181, v202, v214, s[26:27]
	v_cndmask_b32_e64 v204, v202, v216, s[36:37]
	v_cndmask_b32_e64 v203, v202, v218, s[0:1]
	s_addk_i32 s76, 0x1b8
	v_add_u32_e32 v72, s76, v123
	v_mad_i32_i24 v123, v72, s58, v118
	ds_read_b128 v[72:75], v123
	ds_read_b128 v[184:187], v123 offset:64
	ds_read_b128 v[188:191], v123 offset:128
	ds_read_b128 v[228:231], v123 offset:192
	ds_read_b32 v201, v213 offset:1736
	ds_read_b32 v215, v220 offset:1736
	ds_read_b32 v217, v221 offset:1736
	ds_read_b32 v219, v222 offset:1736
	s_waitcnt lgkmcnt(7)
	v_mfma_f32_16x16x32_bf16 v[72:75], v[72:75], v[24:27], 0
	s_waitcnt lgkmcnt(6)
	v_mfma_f32_16x16x32_bf16 v[72:75], v[184:187], v[28:31], v[72:75]
	s_waitcnt lgkmcnt(5)
	v_mfma_f32_16x16x32_bf16 v[72:75], v[188:191], v[36:39], v[72:75]
	s_waitcnt lgkmcnt(4)
	v_mfma_f32_16x16x32_bf16 v[72:75], v[228:231], v[40:43], v[72:75]
	s_nop 7
	s_waitcnt lgkmcnt(0)
	v_fma_f32 v200, v72, s12, v201
	v_fma_f32 v214, v73, s12, v215
	v_fma_f32 v216, v74, s12, v217
	v_fma_f32 v218, v75, s12, v219
	v_cndmask_b32_e64 v206, v202, v200, s[14:15]
	v_cndmask_b32_e64 v205, v202, v214, s[16:17]
	v_cndmask_b32_e64 v208, v202, v216, s[20:21]
	v_cndmask_b32_e64 v207, v202, v218, s[22:23]
	v_add_u32_e32 v72, s76, v130
	v_mad_i32_i24 v118, v72, s58, v118
	ds_read_b128 v[72:75], v118
	ds_read_b128 v[184:187], v118 offset:64
	ds_read_b128 v[188:191], v118 offset:128
	ds_read_b128 v[228:231], v118 offset:192
	ds_read_b32 v201, v223 offset:1736
	ds_read_b32 v215, v224 offset:1736
	ds_read_b32 v217, v225 offset:1736
	ds_read_b32 v219, v226 offset:1736
	s_waitcnt lgkmcnt(7)
	v_mfma_f32_16x16x32_bf16 v[72:75], v[72:75], v[24:27], 0
	s_waitcnt lgkmcnt(6)
	v_mfma_f32_16x16x32_bf16 v[72:75], v[184:187], v[28:31], v[72:75]
	s_waitcnt lgkmcnt(5)
	v_mfma_f32_16x16x32_bf16 v[72:75], v[188:191], v[36:39], v[72:75]
	s_waitcnt lgkmcnt(4)
	v_mfma_f32_16x16x32_bf16 v[72:75], v[228:231], v[40:43], v[72:75]
	s_nop 7
	s_waitcnt lgkmcnt(0)
	v_fma_f32 v200, v72, s12, v201
	v_fma_f32 v214, v73, s12, v215
	v_fma_f32 v216, v74, s12, v217
	v_fma_f32 v218, v75, s12, v219
	v_cndmask_b32_e64 v210, v202, v200, s[24:25]
	v_cndmask_b32_e64 v209, v202, v214, s[26:27]
	v_cndmask_b32_e64 v212, v202, v216, s[36:37]
	v_cndmask_b32_e64 v211, v202, v218, s[0:1]
	s_lshl_b32 s14, s73, 7
	v_max3_f32 v72, v115, s63, v104
	v_max3_f32 v72, v72, v117, v116
	v_max3_f32 v72, v72, v120, v119
	v_max3_f32 v72, v72, v122, v121
	v_max3_f32 v72, v72, v128, v126
	v_max3_f32 v72, v72, v136, v135
	v_max3_f32 v72, v72, v138, v137
	v_max3_f32 v72, v72, v140, v139
	v_max3_f32 v72, v72, v142, v141
	v_max3_f32 v72, v72, v144, v143
	v_max3_f32 v72, v72, v146, v145
	v_max3_f32 v72, v72, v148, v147
	v_max3_f32 v72, v72, v150, v149
	v_max3_f32 v72, v72, v152, v151
	v_max3_f32 v72, v72, v154, v153
	v_max3_f32 v72, v72, v156, v155
	v_max3_f32 v72, v72, v158, v157
	v_max3_f32 v72, v72, v160, v159
	v_max3_f32 v72, v72, v162, v161
	v_max3_f32 v72, v72, v164, v163
	v_max3_f32 v72, v72, v166, v165
	v_max3_f32 v72, v72, v168, v167
	v_max3_f32 v72, v72, v170, v169
	v_max3_f32 v72, v72, v172, v171
	v_max3_f32 v72, v72, v174, v173
	v_max3_f32 v72, v72, v176, v175
	v_max3_f32 v72, v72, v183, v181
	v_max3_f32 v72, v72, v204, v203
	v_and_b32_e32 v74, 64, v107
	v_max3_f32 v72, v72, v206, v205
	v_xor_b32_e32 v73, 16, v107
	v_add_u32_e32 v74, 64, v74
	v_max3_f32 v72, v72, v208, v207
	v_cmp_lt_i32_e32 vcc, v73, v74
	v_max3_f32 v72, v72, v210, v209
	v_max3_f32 v72, v72, v212, v211
	v_cndmask_b32_e32 v73, v107, v73, vcc
	v_lshlrev_b32_e32 v213, 2, v73
	ds_bpermute_b32 v73, v213, v72
	s_waitcnt lgkmcnt(0)
	s_barrier
; template <int L>
; __device__ __forceinline__ void layer_body(const Args& args, LAS unsigned char* lds, const int wave, const int G, const int gw, const int NGW, const int lo, const int hi,
;                                            unsigned char* const ws_kernel, const XcdBarrier& bar, int& pid) {
;     ...
;                 for (; unit < UEND; unit += GH) {
;     ...
;                     float mx = -1e30f;
; #pragma unroll
;                     for (int t = 0; t < 16; ++t)
; #pragma unroll
;                         for (int j = 0; j < 4; ++j) mx = fmaxf(mx, sc[t][j]);
;                     mx = fmaxf(mx, __shfl_xor(mx, 16)); mx = fmaxf(mx, __shfl_xor(mx, 32));
;                     float sum = 0.f;
; #pragma unroll
;                     for (int t = 0; t < 16; ++t)
; #pragma unroll
;                         for (int j = 0; j < 4; ++j) { sc[t][j] = __builtin_amdgcn_exp2f(sc[t][j] - mx); sum += sc[t][j]; }
;                     sum += __shfl_xor(sum, 16); sum += __shfl_xor(sum, 32);
	s_add_i32 s40, s40, s86
	v_max_f32_e32 v73, v73, v73
	v_max_f32_e32 v72, v72, v73
	v_xor_b32_e32 v73, 32, v107
	v_cmp_lt_i32_e32 vcc, v73, v74
	s_cmp_ge_i32 s40, s41
	s_cselect_b64 s[0:1], -1, 0
	v_cndmask_b32_e32 v73, v107, v73, vcc
	v_lshlrev_b32_e32 v214, 2, v73
	ds_bpermute_b32 v73, v214, v72
	s_and_b64 vcc, exec, s[0:1]
	s_waitcnt lgkmcnt(0)
	v_max_f32_e32 v73, v73, v73
	v_max_f32_e32 v215, v72, v73
	v_sub_f32_e32 v72, v115, v215
	v_exp_f32_e32 v190, v72
	v_sub_f32_e32 v72, v104, v215
	v_exp_f32_e32 v198, v72
	v_sub_f32_e32 v72, v117, v215
	v_exp_f32_e32 v194, v72
	v_sub_f32_e32 v72, v116, v215
	v_exp_f32_e32 v200, v72
	v_sub_f32_e32 v72, v120, v215
	v_sub_f32_e32 v104, v209, v215
	v_exp_f32_e32 v196, v72
	v_sub_f32_e32 v72, v119, v215
	v_exp_f32_e32 v119, v104
	v_sub_f32_e32 v104, v212, v215
	v_exp_f32_e32 v201, v72
	v_sub_f32_e32 v72, v122, v215
	v_exp_f32_e32 v116, v104
	v_sub_f32_e32 v104, v211, v215
	v_exp_f32_e32 v199, v72
	v_sub_f32_e32 v72, v121, v215
	v_exp_f32_e32 v121, v104
	v_add_f32_e32 v104, 0, v190
	v_add_f32_e32 v104, v198, v104
	v_add_f32_e32 v104, v194, v104
	v_exp_f32_e32 v202, v72
	v_sub_f32_e32 v72, v128, v215
	v_add_f32_e32 v104, v200, v104
	v_exp_f32_e32 v180, v72
	v_sub_f32_e32 v72, v126, v215
	v_add_f32_e32 v104, v196, v104
	v_exp_f32_e32 v191, v72
	v_sub_f32_e32 v72, v136, v215
	v_add_f32_e32 v104, v201, v104
	v_exp_f32_e32 v186, v72
	v_sub_f32_e32 v72, v135, v215
	v_add_f32_e32 v104, v199, v104
	v_exp_f32_e32 v193, v72
	v_sub_f32_e32 v72, v138, v215
	v_add_f32_e32 v104, v202, v104
	v_exp_f32_e32 v188, v72
	v_sub_f32_e32 v72, v137, v215
	v_add_f32_e32 v104, v180, v104
	v_exp_f32_e32 v195, v72
	v_sub_f32_e32 v72, v140, v215
	v_add_f32_e32 v104, v191, v104
	v_exp_f32_e32 v192, v72
	v_sub_f32_e32 v72, v139, v215
	v_add_f32_e32 v104, v186, v104
	v_exp_f32_e32 v197, v72
	v_sub_f32_e32 v72, v142, v215
	v_add_f32_e32 v104, v193, v104
	v_exp_f32_e32 v177, v72
	v_sub_f32_e32 v72, v141, v215
	v_add_f32_e32 v104, v188, v104
	v_exp_f32_e32 v182, v72
	v_sub_f32_e32 v72, v144, v215
	v_add_f32_e32 v104, v195, v104
	v_exp_f32_e32 v178, v72
	v_sub_f32_e32 v72, v143, v215
	v_add_f32_e32 v104, v192, v104
	v_exp_f32_e32 v185, v72
	v_sub_f32_e32 v72, v146, v215
	v_add_f32_e32 v104, v197, v104
	v_exp_f32_e32 v179, v72
	v_sub_f32_e32 v72, v145, v215
	v_add_f32_e32 v104, v177, v104
	v_exp_f32_e32 v187, v72
	v_sub_f32_e32 v72, v148, v215
	v_add_f32_e32 v104, v182, v104
	v_exp_f32_e32 v184, v72
	v_sub_f32_e32 v72, v147, v215
	v_add_f32_e32 v104, v178, v104
	v_exp_f32_e32 v189, v72
	v_sub_f32_e32 v72, v150, v215
	v_add_f32_e32 v104, v185, v104
	v_exp_f32_e32 v138, v72
	v_sub_f32_e32 v72, v149, v215
	v_add_f32_e32 v104, v179, v104
	v_exp_f32_e32 v146, v72
	v_sub_f32_e32 v72, v152, v215
	v_add_f32_e32 v104, v187, v104
	v_exp_f32_e32 v142, v72
	v_sub_f32_e32 v72, v151, v215
	v_add_f32_e32 v104, v184, v104
	v_exp_f32_e32 v148, v72
	v_sub_f32_e32 v72, v154, v215
	v_add_f32_e32 v104, v189, v104
	v_exp_f32_e32 v144, v72
	v_sub_f32_e32 v72, v153, v215
	v_add_f32_e32 v104, v138, v104
	v_exp_f32_e32 v150, v72
	v_sub_f32_e32 v72, v156, v215
	v_add_f32_e32 v104, v146, v104
	v_exp_f32_e32 v147, v72
	v_sub_f32_e32 v72, v155, v215
	v_add_f32_e32 v104, v142, v104
	v_exp_f32_e32 v152, v72
	v_sub_f32_e32 v72, v158, v215
	v_add_f32_e32 v104, v148, v104
	v_exp_f32_e32 v130, v72
	v_sub_f32_e32 v72, v157, v215
	v_add_f32_e32 v104, v144, v104
	v_exp_f32_e32 v139, v72
	v_sub_f32_e32 v72, v160, v215
	v_add_f32_e32 v104, v150, v104
	v_exp_f32_e32 v134, v72
	v_sub_f32_e32 v72, v159, v215
	v_add_f32_e32 v104, v147, v104
	v_exp_f32_e32 v141, v72
	v_sub_f32_e32 v72, v162, v215
	v_add_f32_e32 v104, v152, v104
	v_exp_f32_e32 v136, v72
	v_sub_f32_e32 v72, v161, v215
	v_add_f32_e32 v104, v130, v104
	v_exp_f32_e32 v143, v72
	v_sub_f32_e32 v72, v164, v215
	v_add_f32_e32 v104, v139, v104
	v_exp_f32_e32 v140, v72
	v_sub_f32_e32 v72, v163, v215
	v_add_f32_e32 v104, v134, v104
	v_exp_f32_e32 v145, v72
	v_sub_f32_e32 v72, v166, v215
	v_add_f32_e32 v104, v141, v104
	v_exp_f32_e32 v122, v72
	v_sub_f32_e32 v72, v165, v215
	v_add_f32_e32 v104, v136, v104
	v_exp_f32_e32 v131, v72
	v_sub_f32_e32 v72, v168, v215
	v_add_f32_e32 v104, v143, v104
	v_exp_f32_e32 v126, v72
	v_sub_f32_e32 v72, v167, v215
	v_add_f32_e32 v104, v140, v104
	v_exp_f32_e32 v133, v72
	v_sub_f32_e32 v72, v170, v215
	v_add_f32_e32 v104, v145, v104
	v_exp_f32_e32 v128, v72
	v_sub_f32_e32 v72, v169, v215
	v_add_f32_e32 v104, v122, v104
	v_exp_f32_e32 v135, v72
	v_sub_f32_e32 v72, v172, v215
	v_add_f32_e32 v104, v131, v104
	v_exp_f32_e32 v132, v72
	v_sub_f32_e32 v72, v171, v215
	v_add_f32_e32 v104, v126, v104
	v_exp_f32_e32 v137, v72
	v_sub_f32_e32 v72, v174, v215
	v_add_f32_e32 v104, v133, v104
	v_exp_f32_e32 v75, v72
	v_sub_f32_e32 v72, v173, v215
	v_add_f32_e32 v104, v128, v104
	v_exp_f32_e32 v123, v72
	v_sub_f32_e32 v72, v176, v215
	v_add_f32_e32 v104, v135, v104
	v_exp_f32_e32 v118, v72
	v_sub_f32_e32 v72, v175, v215
	v_add_f32_e32 v104, v132, v104
	v_exp_f32_e32 v125, v72
	v_sub_f32_e32 v72, v183, v215
	v_add_f32_e32 v104, v137, v104
	v_exp_f32_e32 v120, v72
	v_sub_f32_e32 v72, v181, v215
	v_add_f32_e32 v104, v75, v104
	v_exp_f32_e32 v127, v72
	v_sub_f32_e32 v72, v204, v215
	v_add_f32_e32 v104, v123, v104
	v_exp_f32_e32 v124, v72
	v_sub_f32_e32 v72, v203, v215
	v_add_f32_e32 v104, v118, v104
	v_exp_f32_e32 v129, v72
	v_sub_f32_e32 v72, v206, v215
	v_add_f32_e32 v104, v125, v104
	v_exp_f32_e32 v72, v72
	v_sub_f32_e32 v73, v205, v215
	v_add_f32_e32 v104, v120, v104
	v_exp_f32_e32 v115, v73
	v_sub_f32_e32 v73, v208, v215
	v_add_f32_e32 v104, v127, v104
	v_exp_f32_e32 v73, v73
	v_sub_f32_e32 v74, v207, v215
	v_add_f32_e32 v104, v124, v104
	v_exp_f32_e32 v117, v74
	v_sub_f32_e32 v74, v210, v215
	v_add_f32_e32 v104, v129, v104
	v_exp_f32_e32 v74, v74
	v_add_f32_e32 v104, v72, v104
	v_add_f32_e32 v104, v115, v104
	v_add_f32_e32 v104, v73, v104
	v_add_f32_e32 v104, v117, v104
	v_add_f32_e32 v104, v74, v104
	v_add_f32_e32 v104, v119, v104
	v_add_f32_e32 v104, v116, v104
	v_add_f32_e32 v104, v121, v104
	ds_bpermute_b32 v149, v213, v104
	v_lshlrev_b32_e32 v153, 2, v76
	v_and_b32_e32 v153, 12, v153
	s_waitcnt lgkmcnt(0)
; #define LAS __attribute__((address_space(3)))
; __device__ __forceinline__ unsigned pk2(float lo, float hi) { return f2bf(lo) | (f2bf(hi) << 16); }
; template <int L>
; __device__ __forceinline__ void layer_body(const Args& args, LAS unsigned char* lds, const int wave, const int G, const int gw, const int NGW, const int lo, const int hi,
;                                            unsigned char* const ws_kernel, const XcdBarrier& bar, int& pid) {
;     ...
;                     sum += __shfl_xor(sum, 16); sum += __shfl_xor(sum, 32);
;                     bf16x8 pbf[8];
; #pragma unroll
;                     for (int s = 0; s < 8; ++s) { const f32x4 p0 = sc[2 * s], p1 = sc[2 * s + 1]; v4u w; w.x = pk2(p0[0], p0[1]); w.y = pk2(p0[2], p0[3]); w.z = pk2(p1[0], p1[1]); w.w = pk2(p1[2], p1[3]); pbf[s] = __builtin_bit_cast(bf16x8, w); }
;                     __syncthreads();
; #pragma unroll
;                     for (int i = 0; i < 14; ++i) { const int kid = skey + 32 * i; *(LAS v4u*)(size_t)(IMG + vimg_off(kid, sch)) = rst[i]; }
;                     __syncthreads();
;                     if (unit + GH < UEND) { NA_LOADROWS(unit + GH, rst, D); NA_LOADQ(unit + GH); }
	v_add_f32_e32 v149, v104, v149
	v_lshlrev_b32_e32 v104, 8, v76
	v_bfe_u32 v76, v76, 2, 2
	v_bitop3_b32 v76, v153, v112, v76 bitop3:0x36
	v_lshlrev_b32_e32 v76, 4, v76
	v_add3_u32 v76, v104, 0, v76
	ds_bpermute_b32 v151, v214, v149
	v_add_u32_e32 v104, 0x10000, v76
	s_waitcnt vmcnt(13)
	ds_write_b128 v76, v[4:7]
	s_waitcnt vmcnt(12)
	ds_write_b128 v76, v[0:3] offset:8192
	s_waitcnt vmcnt(11)
	ds_write_b128 v76, v[12:15] offset:16384
	s_waitcnt vmcnt(10)
	ds_write_b128 v76, v[8:11] offset:24576
	s_waitcnt vmcnt(9)
	ds_write_b128 v76, v[20:23] offset:32768
	s_waitcnt vmcnt(8)
	ds_write_b128 v76, v[16:19] offset:40960
	s_waitcnt vmcnt(7)
	ds_write_b128 v76, v[32:35] offset:49152
	s_waitcnt vmcnt(6)
	ds_write_b128 v76, v[44:47] offset:57344
	s_waitcnt vmcnt(5)
	ds_write_b128 v104, v[48:51]
	v_add_u32_e32 v104, 0x12000, v76
	s_waitcnt vmcnt(4)
	ds_write_b128 v104, v[52:55]
	v_add_u32_e32 v104, 0x14000, v76
	s_waitcnt vmcnt(3)
	ds_write_b128 v104, v[56:59]
	v_add_u32_e32 v104, 0x16000, v76
	s_waitcnt vmcnt(2)
	ds_write_b128 v104, v[60:63]
	v_add_u32_e32 v104, 0x18000, v76
	v_add_u32_e32 v76, 0x1a000, v76
	s_waitcnt vmcnt(1)
	ds_write_b128 v104, v[64:67]
	s_waitcnt vmcnt(0)
	ds_write_b128 v76, v[68:71]
	s_waitcnt lgkmcnt(0)
	s_barrier
	s_cbranch_vccnz .LBB0_3408
	s_add_i32 s16, s52, s53
	s_and_b32 s20, s16, 28
	s_add_i32 s22, s56, s57
	v_sub_u32_e64 v1, s20, 1 clamp
	s_and_b32 s16, s22, 0x780
	v_lshlrev_b32_e32 v0, 3, v112
	s_and_b32 s15, s40, 1
	s_max_u32 s21, s20, 4
	v_min_u32_e32 v1, 24, v1
	s_lshl_b32 s23, s16, 1
	s_add_u32 s16, s48, s23
	v_lshlrev_b32_e32 v104, 1, v0
	v_subrev_u32_e32 v0, s21, v1
	s_addc_u32 s17, s49, 0
	v_add_u32_e32 v31, 11, v0
	v_sub_u32_e64 v30, s20, 4 clamp
	v_lshl_add_u64 v[24:25], s[16:17], 0, v[104:105]
	s_and_b32 s21, s22, 0xfffff800
	s_mul_i32 s16, s15, 24
	v_min_i32_e32 v0, v77, v31
	v_min_i32_e32 v2, v79, v31
	v_min_i32_e32 v8, v81, v31
	v_min_i32_e32 v10, v83, v31
	v_min_i32_e32 v16, v85, v31
	v_min_i32_e32 v18, v87, v31
	v_min_i32_e32 v26, v89, v31
	v_min_i32_e32 v28, v91, v31
	s_or_b32 s22, s21, s16
	v_add_lshl_u32 v0, v0, v30, 6
	v_add_lshl_u32 v2, v2, v30, 6
	v_add_lshl_u32 v8, v8, v30, 6
	v_add_lshl_u32 v10, v10, v30, 6
	v_add_lshl_u32 v16, v16, v30, 6
	v_add_lshl_u32 v18, v18, v30, 6
	v_add_lshl_u32 v26, v26, v30, 6
	v_add_lshl_u32 v28, v28, v30, 6
	v_add3_u32 v0, v78, s22, v0
	v_add3_u32 v2, v80, s22, v2
	v_add3_u32 v8, v82, s22, v8
	v_add3_u32 v10, v84, s22, v10
	v_add3_u32 v16, v86, s22, v16
	v_add3_u32 v18, v88, s22, v18
	v_add3_u32 v26, v90, s22, v26
	v_add3_u32 v28, v92, s22, v28
	v_mad_i64_i32 v[0:1], s[16:17], v0, s62, v[24:25]
	v_mad_i64_i32 v[2:3], s[16:17], v2, s62, v[24:25]
	v_mad_i64_i32 v[8:9], s[16:17], v8, s62, v[24:25]
	v_mad_i64_i32 v[10:11], s[16:17], v10, s62, v[24:25]
	v_mad_i64_i32 v[16:17], s[16:17], v16, s62, v[24:25]
	v_mad_i64_i32 v[18:19], s[16:17], v18, s62, v[24:25]
	v_mad_i64_i32 v[26:27], s[16:17], v26, s62, v[24:25]
	v_mad_i64_i32 v[28:29], s[16:17], v28, s62, v[24:25]
	global_load_dwordx4 v[4:7], v[0:1], off
	s_nop 0
	global_load_dwordx4 v[0:3], v[2:3], off
	s_nop 0
	global_load_dwordx4 v[12:15], v[8:9], off
	s_nop 0
	global_load_dwordx4 v[8:11], v[10:11], off
	s_nop 0
	global_load_dwordx4 v[20:23], v[16:17], off
	s_nop 0
	global_load_dwordx4 v[16:19], v[18:19], off
	s_nop 0
	global_load_dwordx4 v[32:35], v[26:27], off
	global_load_dwordx4 v[44:47], v[28:29], off
	v_min_i32_e32 v26, v93, v31
	v_min_i32_e32 v28, v95, v31
	v_add_lshl_u32 v26, v26, v30, 6
	v_add_lshl_u32 v28, v28, v30, 6
	v_add3_u32 v26, v94, s22, v26
	v_add3_u32 v28, v96, s22, v28
	v_mad_i64_i32 v[26:27], s[16:17], v26, s62, v[24:25]
	v_mad_i64_i32 v[28:29], s[16:17], v28, s62, v[24:25]
	global_load_dwordx4 v[48:51], v[26:27], off
	global_load_dwordx4 v[52:55], v[28:29], off
	v_min_i32_e32 v26, v97, v31
	v_min_i32_e32 v28, v100, v31
	v_add_lshl_u32 v26, v26, v30, 6
	v_add_lshl_u32 v28, v28, v30, 6
	v_add3_u32 v26, v98, s22, v26
	v_add3_u32 v28, v101, s22, v28
	v_mad_i64_i32 v[26:27], s[16:17], v26, s62, v[24:25]
	v_mad_i64_i32 v[28:29], s[16:17], v28, s62, v[24:25]
	global_load_dwordx4 v[56:59], v[26:27], off
	global_load_dwordx4 v[60:63], v[28:29], off
	v_min_i32_e32 v26, v102, v31
	v_min_i32_e32 v28, v113, v31
	v_add_lshl_u32 v26, v26, v30, 6
	v_add_lshl_u32 v28, v28, v30, 6
	v_add3_u32 v26, v103, s22, v26
	v_add3_u32 v28, v114, s22, v28
	v_mad_i64_i32 v[26:27], s[16:17], v26, s62, v[24:25]
	v_mad_i64_i32 v[24:25], s[16:17], v28, s62, v[24:25]
	s_add_u32 s16, s44, s23
	s_addc_u32 s17, s45, 0
	s_add_i32 s20, s20, s42
	s_lshl_b32 s20, s20, 6
	s_add_i32 s20, s20, s21
	s_lshl_b32 s15, s15, 5
	s_or_b32 s15, s20, s15
	s_or_b32 s15, s15, s43
	global_load_dwordx4 v[64:67], v[26:27], off
	global_load_dwordx4 v[68:71], v[24:25], off
	v_or_b32_e32 v26, s15, v112
	v_mov_b64_e32 v[24:25], s[16:17]
	v_mad_i64_i32 v[24:25], s[16:17], v26, s62, v[24:25]
	v_lshlrev_b32_e32 v104, 4, v99
	v_lshl_add_u64 v[40:41], v[24:25], 0, v[104:105]
	global_load_dwordx4 v[24:27], v[40:41], off
	global_load_dwordx4 v[28:31], v[40:41], off offset:64
	global_load_dwordx4 v[36:39], v[40:41], off offset:128
	s_nop 0
	global_load_dwordx4 v[40:43], v[40:41], off offset:192
	s_branch .LBB0_3408
